# router / norm / final-row butterflies: in-row xor steps by DPP instead of ds_bpermute (bitwise identical)
# baseline (speedup 1.0000x reference)
.LBB0_223:
	v_lshl_add_u64 v[46:47], s[30:31], 0, v[78:79]
	v_lshl_add_u64 v[10:11], s[28:29], 0, v[74:75]
	v_add_co_u32_e64 v102, s[6:7], s36, v46
	v_lshl_add_u64 v[12:13], s[26:27], 0, v[74:75]
	ds_read_b128 v[2:5], v1
	ds_read_b128 v[6:9], v1 offset:8192
	v_lshl_add_u64 v[48:49], s[24:25], 0, v[78:79]
	global_load_dwordx4 v[42:45], v[10:11], off
	global_load_dwordx4 v[38:41], v[10:11], off offset:1024
	global_load_dwordx4 v[34:37], v[10:11], off offset:2048
	global_load_dwordx4 v[30:33], v[10:11], off offset:3072
	global_load_dwordx4 v[26:29], v[12:13], off
	global_load_dwordx4 v[22:25], v[12:13], off offset:1024
	global_load_dwordx4 v[18:21], v[12:13], off offset:2048
	global_load_dwordx4 v[14:17], v[12:13], off offset:3072
	v_add_co_u32_e32 v10, vcc, 0x1000, v10
	v_addc_co_u32_e64 v103, s[6:7], 0, v47, s[6:7]
	v_add_co_u32_e64 v76, s[6:7], s36, v48
	v_addc_co_u32_e32 v11, vcc, 0, v11, vcc
	s_nop 0
	v_addc_co_u32_e64 v77, s[6:7], 0, v49, s[6:7]
	global_load_dwordx4 v[70:73], v[10:11], off
	global_load_dwordx4 v[62:65], v[10:11], off offset:1024
	global_load_dwordx4 v[46:49], v[10:11], off offset:3072
	global_load_dwordx4 v[66:69], v[10:11], off offset:2048
	v_add_co_u32_e32 v54, vcc, s33, v12
	v_mov_b32_e32 v117, 0
	s_nop 0
	v_addc_co_u32_e32 v55, vcc, 0, v13, vcc
	global_load_dwordx4 v[58:61], v[54:55], off
	global_load_dwordx4 v[50:53], v[54:55], off offset:1024
	global_load_dwordx4 v[10:13], v[54:55], off offset:3072
	s_nop 0
	global_load_dwordx4 v[54:57], v[54:55], off offset:2048
	v_mov_b32_e32 v118, 0
	v_mov_b32_e32 v119, 0
	v_mov_b32_e32 v120, 0
	v_mov_b32_e32 v121, 0
	v_mov_b32_e32 v122, 0
	v_mov_b32_e32 v123, 0
	v_mov_b32_e32 v124, 0
	v_mov_b32_e32 v125, 0
	v_mov_b32_e32 v126, 0
	v_mov_b32_e32 v127, 0
	v_mov_b32_e32 v128, 0
	v_mov_b32_e32 v129, 0
	v_mov_b32_e32 v130, 0
	s_add_i32 s21, s21, 16
	v_mov_b32_e32 v131, 0
	v_mov_b32_e32 v132, 0
	s_add_u32 s24, s24, 0x8000
	s_addc_u32 s25, s25, 0
	s_add_u32 s26, s26, 0x20000
	s_addc_u32 s27, s27, 0
	s_add_u32 s28, s28, 0x20000
	s_addc_u32 s29, s29, 0
	s_add_u32 s30, s30, 0x8000
	s_addc_u32 s31, s31, 0
	s_cmp_lt_u32 s21, 48
	s_waitcnt vmcnt(15)
	v_mov_b32_e32 v136, v43
	s_waitcnt vmcnt(14)
	v_mov_b32_e32 v137, v39
	v_mov_b32_e32 v140, v45
	v_mov_b32_e32 v141, v41
	v_mov_b32_e32 v134, v42
	v_mov_b32_e32 v135, v38
	v_mov_b32_e32 v138, v44
	v_mov_b32_e32 v139, v40
	s_waitcnt vmcnt(13)
	v_pk_mul_f32 v[142:143], v[36:37], v[36:37]
	v_pk_mul_f32 v[144:145], v[34:35], v[34:35]
	s_waitcnt vmcnt(12)
	v_mul_f32_e32 v146, v31, v31
	v_mul_f32_e32 v148, v33, v33
	s_waitcnt vmcnt(11)
	v_mov_b32_e32 v152, v27
	s_waitcnt vmcnt(10)
	v_mov_b32_e32 v153, v23
	v_mov_b32_e32 v156, v29
	v_mov_b32_e32 v157, v25
	v_pk_mul_f32 v[136:137], v[136:137], v[136:137]
	v_pk_mul_f32 v[140:141], v[140:141], v[140:141]
	v_mov_b32_e32 v150, v26
	v_mov_b32_e32 v151, v22
	v_mov_b32_e32 v154, v28
	v_mov_b32_e32 v155, v24
	s_waitcnt vmcnt(9)
	v_pk_mul_f32 v[158:159], v[20:21], v[20:21]
	v_pk_mul_f32 v[160:161], v[18:19], v[18:19]
	s_waitcnt vmcnt(8)
	v_mul_f32_e32 v162, v15, v15
	v_pk_mov_b32 v[166:167], v[144:145], v[142:143] op_sel:[1,0]
	v_mov_b32_e32 v145, v143
	v_pk_fma_f32 v[142:143], v[30:31], v[30:31], v[146:147] op_sel_hi:[1,1,0]
	v_pk_fma_f32 v[146:147], v[32:33], v[32:33], v[148:149] op_sel_hi:[1,1,0]
	v_pk_mul_f32 v[148:149], v[152:153], v[152:153]
	v_pk_mul_f32 v[152:153], v[156:157], v[156:157]
	v_pk_fma_f32 v[134:135], v[134:135], v[134:135], v[136:137]
	v_pk_fma_f32 v[136:137], v[138:139], v[138:139], v[140:141]
	v_mul_f32_e32 v164, v17, v17
	v_pk_mov_b32 v[156:157], v[160:161], v[158:159] op_sel:[1,0]
	v_mov_b32_e32 v161, v159
	v_pk_fma_f32 v[158:159], v[14:15], v[14:15], v[162:163] op_sel_hi:[1,1,0]
	v_pk_add_f32 v[138:139], v[166:167], v[144:145]
	s_waitcnt vmcnt(6)
	v_pk_mul_f32 v[140:141], v[64:65], v[64:65]
	v_pk_mul_f32 v[144:145], v[62:63], v[62:63]
	v_pk_fma_f32 v[148:149], v[150:151], v[150:151], v[148:149]
	v_pk_fma_f32 v[150:151], v[154:155], v[154:155], v[152:153]
	v_pk_add_f32 v[134:135], v[134:135], v[136:137]
	v_pk_fma_f32 v[162:163], v[16:17], v[16:17], v[164:165] op_sel_hi:[1,1,0]
	v_mul_f32_e32 v133, v70, v70
	v_mul_f32_e32 v159, v71, v71
	s_waitcnt vmcnt(5)
	v_mul_f32_e32 v165, v46, v46
	v_mul_f32_e32 v167, v47, v47
	s_waitcnt vmcnt(4)
	v_mul_f32_e32 v164, v67, v67
	v_mul_f32_e32 v166, v69, v69
	v_pk_add_f32 v[152:153], v[156:157], v[160:161]
	v_pk_add_f32 v[136:137], v[138:139], v[138:139] op_sel:[0,1] op_sel_hi:[1,0]
	v_pk_mov_b32 v[138:139], v[144:145], v[140:141] op_sel:[1,0]
	v_mov_b32_e32 v145, v141
	v_pk_add_f32 v[148:149], v[148:149], v[150:151]
	v_pk_add_f32 v[134:135], v[134:135], v[134:135] op_sel:[0,1] op_sel_hi:[1,0]
	v_mul_f32_e32 v143, v72, v72
	v_mul_f32_e32 v147, v73, v73
	v_mul_f32_e32 v163, v48, v48
	v_mul_f32_e32 v168, v49, v49
	v_pk_fma_f32 v[140:141], v[66:67], v[66:67], v[164:165] op_sel_hi:[1,1,0]
	v_pk_fma_f32 v[154:155], v[68:69], v[68:69], v[166:167] op_sel_hi:[1,1,0]
	s_waitcnt vmcnt(3)
	v_mul_f32_e32 v161, v58, v58
	v_mul_f32_e32 v166, v59, v59
	v_mul_f32_e32 v169, v60, v60
	v_mul_f32_e32 v170, v61, v61
	v_pk_add_f32 v[150:151], v[152:153], v[152:153] op_sel:[0,1] op_sel_hi:[1,0]
	v_mov_b32_e32 v137, v159
	v_pk_add_f32 v[138:139], v[138:139], v[144:145]
	v_pk_add_f32 v[144:145], v[148:149], v[148:149] op_sel:[0,1] op_sel_hi:[1,0]
	v_mov_b32_e32 v135, v133
	s_waitcnt vmcnt(2)
	v_pk_mul_f32 v[152:153], v[52:53], v[52:53]
	v_pk_mul_f32 v[156:157], v[50:51], v[50:51]
	v_pk_add_f32 v[142:143], v[142:143], v[146:147]
	v_mov_b32_e32 v141, v163
	v_mov_b32_e32 v155, v168
	v_mov_b32_e32 v151, v166
	v_mov_b32_e32 v159, v169
	v_mov_b32_e32 v163, v170
	v_mov_b32_e32 v145, v161
	v_pk_add_f32 v[134:135], v[134:135], v[136:137]
	v_pk_mov_b32 v[146:147], v[156:157], v[152:153] op_sel:[1,0]
	v_mov_b32_e32 v157, v153
	v_pk_add_f32 v[140:141], v[140:141], v[154:155]
	v_pk_add_f32 v[154:155], v[158:159], v[162:163]
	v_pk_add_f32 v[136:137], v[144:145], v[150:151]
	v_pk_add_f32 v[134:135], v[134:135], v[142:143]
	s_waitcnt vmcnt(0)
	v_mul_f32_e32 v160, v55, v55
	v_mul_f32_e32 v164, v57, v57
	v_pk_add_f32 v[138:139], v[138:139], v[138:139] op_sel:[0,1] op_sel_hi:[1,0]
	v_pk_add_f32 v[146:147], v[146:147], v[156:157]
	v_pk_add_f32 v[136:137], v[136:137], v[154:155]
	v_pk_add_f32 v[134:135], v[134:135], v[134:135] op_sel:[0,1] op_sel_hi:[1,0]
	v_mul_f32_e32 v171, v10, v10
	v_mul_f32_e32 v172, v11, v11
	v_mul_f32_e32 v173, v12, v12
	v_mul_f32_e32 v174, v13, v13
	v_pk_fma_f32 v[148:149], v[54:55], v[54:55], v[160:161] op_sel_hi:[1,1,0]
	v_pk_fma_f32 v[152:153], v[56:57], v[56:57], v[164:165] op_sel_hi:[1,1,0]
	v_mov_b32_e32 v139, v167
	v_pk_add_f32 v[144:145], v[146:147], v[146:147] op_sel:[0,1] op_sel_hi:[1,0]
	v_pk_add_f32 v[136:137], v[136:137], v[136:137] op_sel:[0,1] op_sel_hi:[1,0]
	v_mov_b32_e32 v135, v165
	v_mov_b32_e32 v149, v173
	v_mov_b32_e32 v153, v174
	v_mov_b32_e32 v145, v172
	v_mov_b32_e32 v137, v171
	v_pk_add_f32 v[134:135], v[134:135], v[138:139]
	v_pk_add_f32 v[146:147], v[148:149], v[152:153]
	v_pk_add_f32 v[136:137], v[136:137], v[144:145]
	v_pk_add_f32 v[134:135], v[134:135], v[140:141]
	v_pk_add_f32 v[136:137], v[136:137], v[146:147]
	v_add_f32_e32 v133, v134, v135
	v_add_f32_e32 v134, v136, v137
	s_waitcnt lgkmcnt(1)
	s_nop 1
	v_add_f32_dpp v133, v133, v133 quad_perm:[1,0,3,2] row_mask:0xf bank_mask:0xf
	s_waitcnt lgkmcnt(0)
	s_nop 1
	v_add_f32_dpp v134, v134, v134 quad_perm:[1,0,3,2] row_mask:0xf bank_mask:0xf
	s_waitcnt lgkmcnt(1)
	s_nop 1
	v_add_f32_dpp v133, v133, v133 quad_perm:[2,3,0,1] row_mask:0xf bank_mask:0xf
	s_waitcnt lgkmcnt(0)
	s_nop 1
	v_add_f32_dpp v134, v134, v134 quad_perm:[2,3,0,1] row_mask:0xf bank_mask:0xf
	s_waitcnt lgkmcnt(1)
	s_nop 1
	v_add_f32_dpp v133, v133, v133 row_half_mirror row_mask:0xf bank_mask:0xf
	s_waitcnt lgkmcnt(0)
	s_nop 1
	v_add_f32_dpp v134, v134, v134 row_half_mirror row_mask:0xf bank_mask:0xf
	s_waitcnt lgkmcnt(1)
	s_nop 1
	v_add_f32_dpp v133, v133, v133 row_mirror row_mask:0xf bank_mask:0xf
	s_waitcnt lgkmcnt(0)
	s_nop 1
	v_add_f32_dpp v134, v134, v134 row_mirror row_mask:0xf bank_mask:0xf
	ds_bpermute_b32 v135, v115, v133
	ds_bpermute_b32 v136, v115, v134
	s_waitcnt lgkmcnt(1)
	v_add_f32_e32 v133, v133, v135
	s_waitcnt lgkmcnt(0)
	v_add_f32_e32 v134, v134, v136
	ds_bpermute_b32 v135, v116, v133
	ds_bpermute_b32 v136, v116, v134
	s_waitcnt lgkmcnt(1)
	v_add_f32_e32 v133, v133, v135
	s_waitcnt lgkmcnt(0)
	v_add_f32_e32 v134, v134, v136
	v_fmamk_f32 v133, v133, 0x3a000000, v108
	v_fmamk_f32 v134, v134, 0x3a000000, v108
	v_mul_f32_e32 v135, 0x4f800000, v133
	v_cmp_gt_f32_e64 s[6:7], s34, v133
	v_mul_f32_e32 v136, 0x4f800000, v134
	v_cmp_gt_f32_e32 vcc, s34, v134
	v_cndmask_b32_e64 v133, v133, v135, s[6:7]
	v_sqrt_f32_e32 v135, v133
	v_cndmask_b32_e32 v134, v134, v136, vcc
	v_sqrt_f32_e32 v136, v134
	v_add_u32_e32 v137, -1, v135
	v_add_u32_e32 v138, 1, v135
	v_add_u32_e32 v139, -1, v136
	v_fma_f32 v141, -v137, v135, v133
	v_add_u32_e32 v140, 1, v136
	v_fma_f32 v142, -v138, v135, v133
	v_fma_f32 v143, -v139, v136, v134
	v_cmp_ge_f32_e64 s[8:9], 0, v141
	v_fma_f32 v144, -v140, v136, v134
	v_cmp_lt_f32_e64 s[10:11], 0, v142
	v_cndmask_b32_e64 v135, v135, v137, s[8:9]
	v_cmp_ge_f32_e64 s[8:9], 0, v143
	v_cndmask_b32_e64 v135, v135, v138, s[10:11]
	v_mul_f32_e32 v137, 0x37800000, v135
	v_cndmask_b32_e64 v136, v136, v139, s[8:9]
	v_cmp_lt_f32_e64 s[8:9], 0, v144
	v_cndmask_b32_e64 v135, v135, v137, s[6:7]
	v_cmp_class_f32_e64 s[6:7], v133, v109
	v_cndmask_b32_e64 v136, v136, v140, s[8:9]
	v_mul_f32_e32 v138, 0x37800000, v136
	v_cndmask_b32_e32 v136, v136, v138, vcc
	v_cmp_class_f32_e32 vcc, v134, v109
	v_cndmask_b32_e64 v133, v135, v133, s[6:7]
	s_nop 0
	v_cndmask_b32_e32 v135, v136, v134, vcc
	v_div_scale_f32 v134, s[6:7], v133, v133, 1.0
	v_rcp_f32_e32 v139, v134
	v_div_scale_f32 v136, vcc, 1.0, v133, 1.0
	v_div_scale_f32 v137, s[6:7], v135, v135, 1.0
	v_fma_f32 v141, -v134, v139, 1.0
	v_fmac_f32_e32 v139, v141, v139
	v_mul_f32_e32 v141, v136, v139
	v_fma_f32 v143, -v134, v141, v136
	v_fmac_f32_e32 v141, v143, v139
	v_fma_f32 v134, -v134, v141, v136
	v_div_fmas_f32 v134, v134, v139, v141
	v_div_fixup_f32 v134, v134, v133, 1.0
	v_pk_mul_f32 v[42:43], v[42:43], v[134:135] op_sel_hi:[1,0]
	v_pk_mul_f32 v[44:45], v[44:45], v[134:135] op_sel_hi:[1,0]
	v_pk_fma_f32 v[2:3], v[2:3], v[42:43], v[6:7]
	v_pk_fma_f32 v[44:45], v[4:5], v[44:45], v[8:9]
	v_cvt_pk_bf16_f32 v4, v2, v3
	v_cvt_pk_fp8_f32 v117, v2, v3
	v_cvt_pk_bf16_f32 v4, v44, v45
	ds_read_b128 v[2:5], v1 offset:1024
	ds_read_b128 v[6:9], v1 offset:9216
	v_pk_mul_f32 v[38:39], v[38:39], v[134:135] op_sel_hi:[1,0]
	v_cvt_pk_fp8_f32 v117, v44, v45 op_sel:[0,0,1]
	v_pk_mul_f32 v[40:41], v[40:41], v[134:135] op_sel_hi:[1,0]
	v_pk_mul_f32 v[34:35], v[34:35], v[134:135] op_sel_hi:[1,0]
	s_waitcnt lgkmcnt(0)
	v_pk_fma_f32 v[2:3], v[2:3], v[38:39], v[6:7]
	v_pk_fma_f32 v[40:41], v[4:5], v[40:41], v[8:9]
	v_cvt_pk_fp8_f32 v118, v2, v3
	global_store_dword v[102:103], v117, off
	v_cvt_pk_bf16_f32 v2, v2, v3
	v_pk_mul_f32 v[36:37], v[36:37], v[134:135] op_sel_hi:[1,0]
	v_cvt_pk_bf16_f32 v2, v40, v41
	ds_read_b128 v[2:5], v1 offset:2048
	ds_read_b128 v[6:9], v1 offset:10240
	v_cvt_pk_fp8_f32 v118, v40, v41 op_sel:[0,0,1]
	v_pk_mul_f32 v[30:31], v[30:31], v[134:135] op_sel_hi:[1,0]
	v_pk_mul_f32 v[32:33], v[32:33], v[134:135] op_sel_hi:[1,0]
	v_pk_mul_f32 v[70:71], v[70:71], v[134:135] op_sel_hi:[1,0]
	s_waitcnt lgkmcnt(0)
	v_pk_fma_f32 v[36:37], v[36:37], v[4:5], v[8:9]
	v_pk_fma_f32 v[2:3], v[34:35], v[2:3], v[6:7]
	global_store_dword v[102:103], v118, off offset:256
	v_cvt_pk_bf16_f32 v4, v2, v3
	v_cvt_pk_fp8_f32 v119, v2, v3
	v_cvt_pk_bf16_f32 v4, v36, v37
	ds_read_b128 v[2:5], v1 offset:3072
	ds_read_b128 v[6:9], v1 offset:11264
	v_pk_mul_f32 v[72:73], v[72:73], v[134:135] op_sel_hi:[1,0]
	v_cvt_pk_fp8_f32 v119, v36, v37 op_sel:[0,0,1]
	v_pk_mul_f32 v[62:63], v[62:63], v[134:135] op_sel_hi:[1,0]
	v_pk_mul_f32 v[64:65], v[64:65], v[134:135] op_sel_hi:[1,0]
	s_waitcnt lgkmcnt(0)
	v_pk_fma_f32 v[2:3], v[30:31], v[2:3], v[6:7]
	v_pk_fma_f32 v[32:33], v[32:33], v[4:5], v[8:9]
	v_cvt_pk_fp8_f32 v120, v2, v3
	global_store_dword v[102:103], v119, off offset:512
	v_cvt_pk_bf16_f32 v2, v2, v3
	v_pk_mul_f32 v[66:67], v[66:67], v[134:135] op_sel_hi:[1,0]
	v_cvt_pk_bf16_f32 v2, v32, v33
	ds_read_b128 v[2:5], v1 offset:4096
	ds_read_b128 v[6:9], v1 offset:12288
	v_cvt_pk_fp8_f32 v120, v32, v33 op_sel:[0,0,1]
	v_pk_mul_f32 v[68:69], v[68:69], v[134:135] op_sel_hi:[1,0]
	v_rcp_f32_e32 v140, v137
	v_pk_mul_f32 v[46:47], v[46:47], v[134:135] op_sel_hi:[1,0]
	s_waitcnt lgkmcnt(0)
	v_pk_fma_f32 v[30:31], v[72:73], v[4:5], v[8:9]
	v_pk_fma_f32 v[2:3], v[70:71], v[2:3], v[6:7]
	global_store_dword v[102:103], v120, off offset:768
	v_cvt_pk_bf16_f32 v4, v2, v3
	v_cvt_pk_fp8_f32 v121, v2, v3
	v_cvt_pk_bf16_f32 v4, v30, v31
	ds_read_b128 v[2:5], v1 offset:5120
	ds_read_b128 v[6:9], v1 offset:13312
	v_fma_f32 v142, -v137, v140, 1.0
	v_cvt_pk_fp8_f32 v121, v30, v31 op_sel:[0,0,1]
	v_div_scale_f32 v138, s[6:7], 1.0, v135, 1.0
	s_waitcnt lgkmcnt(0)
	v_pk_fma_f32 v[2:3], v[62:63], v[2:3], v[6:7]
	v_pk_fma_f32 v[30:31], v[64:65], v[4:5], v[8:9]
	v_cvt_pk_fp8_f32 v122, v2, v3
	global_store_dword v[102:103], v121, off offset:1024
	v_cvt_pk_bf16_f32 v2, v2, v3
	v_fmac_f32_e32 v140, v142, v140
	v_cvt_pk_bf16_f32 v2, v30, v31
	ds_read_b128 v[2:5], v1 offset:6144
	ds_read_b128 v[6:9], v1 offset:14336
	v_cvt_pk_fp8_f32 v122, v30, v31 op_sel:[0,0,1]
	v_mul_f32_e32 v142, v138, v140
	v_pk_mul_f32 v[48:49], v[48:49], v[134:135] op_sel_hi:[1,0]
	v_fma_f32 v144, -v137, v142, v138
	s_waitcnt lgkmcnt(0)
	v_pk_fma_f32 v[30:31], v[68:69], v[4:5], v[8:9]
	v_pk_fma_f32 v[2:3], v[66:67], v[2:3], v[6:7]
	global_store_dword v[102:103], v122, off offset:1280
	v_cvt_pk_bf16_f32 v4, v2, v3
	v_cvt_pk_fp8_f32 v123, v2, v3
	v_cvt_pk_bf16_f32 v4, v30, v31
	ds_read_b128 v[2:5], v1 offset:7168
	ds_read_b128 v[6:9], v1 offset:15360
	v_fmac_f32_e32 v142, v144, v140
	v_cvt_pk_fp8_f32 v123, v30, v31 op_sel:[0,0,1]
	v_fma_f32 v136, -v137, v142, v138
	s_mov_b64 vcc, s[6:7]
	s_waitcnt lgkmcnt(0)
	v_pk_fma_f32 v[2:3], v[46:47], v[2:3], v[6:7]
	v_pk_fma_f32 v[30:31], v[48:49], v[4:5], v[8:9]
	v_cvt_pk_fp8_f32 v124, v2, v3
	global_store_dword v[102:103], v123, off offset:1536
	v_cvt_pk_bf16_f32 v2, v2, v3
	v_div_fmas_f32 v133, v136, v140, v142
	v_cvt_pk_bf16_f32 v2, v30, v31
	ds_read_b128 v[2:5], v1
	ds_read_b128 v[6:9], v1 offset:8192
	v_cvt_pk_fp8_f32 v124, v30, v31 op_sel:[0,0,1]
	v_div_fixup_f32 v134, v133, v135, 1.0
	v_pk_mul_f32 v[26:27], v[26:27], v[134:135] op_sel_hi:[1,0]
	v_pk_mul_f32 v[28:29], v[28:29], v[134:135] op_sel_hi:[1,0]
	s_waitcnt lgkmcnt(0)
	v_pk_fma_f32 v[2:3], v[2:3], v[26:27], v[6:7]
	v_pk_fma_f32 v[28:29], v[4:5], v[28:29], v[8:9]
	global_store_dword v[102:103], v124, off offset:1792
	v_cvt_pk_bf16_f32 v4, v2, v3
	v_cvt_pk_fp8_f32 v125, v2, v3
	v_cvt_pk_bf16_f32 v4, v28, v29
	ds_read_b128 v[2:5], v1 offset:1024
	ds_read_b128 v[6:9], v1 offset:9216
	v_pk_mul_f32 v[22:23], v[22:23], v[134:135] op_sel_hi:[1,0]
	v_cvt_pk_fp8_f32 v125, v28, v29 op_sel:[0,0,1]
	v_pk_mul_f32 v[24:25], v[24:25], v[134:135] op_sel_hi:[1,0]
	v_pk_mul_f32 v[18:19], v[18:19], v[134:135] op_sel_hi:[1,0]
	s_waitcnt lgkmcnt(0)
	v_pk_fma_f32 v[2:3], v[2:3], v[22:23], v[6:7]
	v_pk_fma_f32 v[24:25], v[4:5], v[24:25], v[8:9]
	v_cvt_pk_fp8_f32 v126, v2, v3
	global_store_dword v[76:77], v125, off
	v_cvt_pk_bf16_f32 v2, v2, v3
	v_pk_mul_f32 v[20:21], v[20:21], v[134:135] op_sel_hi:[1,0]
	v_cvt_pk_bf16_f32 v2, v24, v25
	ds_read_b128 v[2:5], v1 offset:2048
	ds_read_b128 v[6:9], v1 offset:10240
	v_cvt_pk_fp8_f32 v126, v24, v25 op_sel:[0,0,1]
	v_pk_mul_f32 v[14:15], v[14:15], v[134:135] op_sel_hi:[1,0]
	v_pk_mul_f32 v[16:17], v[16:17], v[134:135] op_sel_hi:[1,0]
	v_pk_mul_f32 v[42:43], v[58:59], v[134:135] op_sel_hi:[1,0]
	s_waitcnt lgkmcnt(0)
	v_pk_fma_f32 v[20:21], v[20:21], v[4:5], v[8:9]
	v_pk_fma_f32 v[2:3], v[18:19], v[2:3], v[6:7]
	global_store_dword v[76:77], v126, off offset:256
	v_cvt_pk_bf16_f32 v4, v2, v3
	v_cvt_pk_fp8_f32 v127, v2, v3
	v_cvt_pk_bf16_f32 v4, v20, v21
	ds_read_b128 v[2:5], v1 offset:3072
	ds_read_b128 v[6:9], v1 offset:11264
	v_pk_mul_f32 v[58:59], v[60:61], v[134:135] op_sel_hi:[1,0]
	v_cvt_pk_fp8_f32 v127, v20, v21 op_sel:[0,0,1]
	v_pk_mul_f32 v[50:51], v[50:51], v[134:135] op_sel_hi:[1,0]
	v_pk_mul_f32 v[52:53], v[52:53], v[134:135] op_sel_hi:[1,0]
	s_waitcnt lgkmcnt(0)
	v_pk_fma_f32 v[2:3], v[14:15], v[2:3], v[6:7]
	v_pk_fma_f32 v[16:17], v[16:17], v[4:5], v[8:9]
	v_cvt_pk_fp8_f32 v128, v2, v3
	global_store_dword v[76:77], v127, off offset:512
	v_cvt_pk_bf16_f32 v2, v2, v3
	v_pk_mul_f32 v[54:55], v[54:55], v[134:135] op_sel_hi:[1,0]
	v_cvt_pk_bf16_f32 v2, v16, v17
	ds_read_b128 v[2:5], v1 offset:4096
	ds_read_b128 v[6:9], v1 offset:12288
	v_cvt_pk_fp8_f32 v128, v16, v17 op_sel:[0,0,1]
	v_pk_mul_f32 v[56:57], v[56:57], v[134:135] op_sel_hi:[1,0]
	v_pk_mul_f32 v[10:11], v[10:11], v[134:135] op_sel_hi:[1,0]
	v_pk_mul_f32 v[12:13], v[12:13], v[134:135] op_sel_hi:[1,0]
	s_waitcnt lgkmcnt(0)
	v_pk_fma_f32 v[14:15], v[58:59], v[4:5], v[8:9]
	v_pk_fma_f32 v[2:3], v[42:43], v[2:3], v[6:7]
	global_store_dword v[76:77], v128, off offset:768
	v_cvt_pk_bf16_f32 v4, v2, v3
	v_cvt_pk_fp8_f32 v129, v2, v3
	v_cvt_pk_bf16_f32 v4, v14, v15
	ds_read_b128 v[2:5], v1 offset:5120
	ds_read_b128 v[6:9], v1 offset:13312
	v_cvt_pk_fp8_f32 v129, v14, v15 op_sel:[0,0,1]
	s_waitcnt lgkmcnt(0)
	v_pk_fma_f32 v[2:3], v[50:51], v[2:3], v[6:7]
	s_nop 0
	v_cvt_pk_fp8_f32 v130, v2, v3
	v_pk_fma_f32 v[14:15], v[52:53], v[4:5], v[8:9]
	global_store_dword v[76:77], v129, off offset:1024
	v_cvt_pk_bf16_f32 v2, v2, v3
	v_cvt_pk_fp8_f32 v130, v14, v15 op_sel:[0,0,1]
	v_cvt_pk_bf16_f32 v2, v14, v15
	ds_read_b128 v[2:5], v1 offset:6144
	ds_read_b128 v[6:9], v1 offset:14336
	global_store_dword v[76:77], v130, off offset:1280
	s_waitcnt lgkmcnt(0)
	v_pk_fma_f32 v[14:15], v[56:57], v[4:5], v[8:9]
	v_pk_fma_f32 v[16:17], v[54:55], v[2:3], v[6:7]
	s_nop 0
	v_cvt_pk_bf16_f32 v2, v16, v17
	v_cvt_pk_fp8_f32 v131, v16, v17
	v_cvt_pk_bf16_f32 v2, v14, v15
	ds_read_b128 v[2:5], v1 offset:7168
	ds_read_b128 v[6:9], v1 offset:15360
	v_cvt_pk_fp8_f32 v131, v14, v15 op_sel:[0,0,1]
	s_waitcnt lgkmcnt(0)
	v_pk_fma_f32 v[2:3], v[10:11], v[2:3], v[6:7]
	s_nop 0
	v_cvt_pk_fp8_f32 v132, v2, v3
	v_pk_fma_f32 v[4:5], v[12:13], v[4:5], v[8:9]
	global_store_dword v[76:77], v131, off offset:1536
	v_cvt_pk_bf16_f32 v2, v2, v3
	v_cvt_pk_fp8_f32 v132, v4, v5 op_sel:[0,0,1]
	v_cvt_pk_bf16_f32 v2, v4, v5
	global_store_dword v[76:77], v132, off offset:1792
	s_cbranch_scc1 .LBB0_223
	s_branch .LBB0_218

.LBB0_1157:
	s_lshl_b32 s35, s37, 4
	s_add_i32 s10, s36, s35
	s_ashr_i32 s11, s10, 31
	s_lshl_b64 s[38:39], s[10:11], 13
	v_lshl_add_u64 v[34:35], v[114:115], 0, s[38:39]
	global_load_dwordx4 v[96:99], v[34:35], off
	global_load_dwordx4 v[92:95], v[34:35], off offset:1024
	global_load_dwordx4 v[88:91], v[34:35], off offset:2048
	global_load_dwordx4 v[84:87], v[34:35], off offset:3072
	s_or_b32 s10, s10, 1
	s_ashr_i32 s11, s10, 31
	s_lshl_b64 s[10:11], s[10:11], 13
	v_add_co_u32_e32 v34, vcc, 0x1000, v34
	v_lshl_add_u64 v[36:37], v[114:115], 0, s[10:11]
	s_nop 0
	v_addc_co_u32_e32 v35, vcc, 0, v35, vcc
	global_load_dwordx4 v[64:67], v[36:37], off
	global_load_dwordx4 v[60:63], v[36:37], off offset:1024
	global_load_dwordx4 v[80:83], v[34:35], off
	global_load_dwordx4 v[76:79], v[34:35], off offset:1024
	global_load_dwordx4 v[68:71], v[34:35], off offset:3072
	global_load_dwordx4 v[72:75], v[34:35], off offset:2048
	global_load_dwordx4 v[56:59], v[36:37], off offset:2048
	global_load_dwordx4 v[52:55], v[36:37], off offset:3072
	v_add_co_u32_e32 v34, vcc, s30, v36
	s_add_i32 s35, s35, s34
	s_nop 0
	v_addc_co_u32_e32 v35, vcc, 0, v37, vcc
	global_load_dwordx4 v[48:51], v[34:35], off
	global_load_dwordx4 v[42:45], v[34:35], off offset:1024
	global_load_dwordx4 v[38:41], v[34:35], off offset:2048
	s_nop 0
	global_load_dwordx4 v[34:37], v[34:35], off offset:3072
	s_mov_b32 s2, 0
	s_waitcnt vmcnt(15)
	v_mov_b32_e32 v190, v97
	s_waitcnt vmcnt(14)
	v_mov_b32_e32 v191, v93
	v_mov_b32_e32 v194, v99
	v_mov_b32_e32 v195, v95
	v_mov_b32_e32 v46, v96
	v_mov_b32_e32 v47, v92
	v_mov_b32_e32 v192, v98
	v_mov_b32_e32 v193, v94
	s_waitcnt vmcnt(13)
	v_pk_mul_f32 v[196:197], v[90:91], v[90:91]
	v_pk_mul_f32 v[198:199], v[88:89], v[88:89]
	v_pk_mul_f32 v[190:191], v[190:191], v[190:191]
	v_pk_mul_f32 v[194:195], v[194:195], v[194:195]
	v_pk_mov_b32 v[202:203], v[198:199], v[196:197] op_sel:[1,0]
	v_mov_b32_e32 v199, v197
	v_pk_fma_f32 v[46:47], v[46:47], v[46:47], v[190:191]
	v_pk_fma_f32 v[190:191], v[192:193], v[192:193], v[194:195]
	s_waitcnt vmcnt(12)
	v_mul_f32_e32 v100, v85, v85
	v_mul_f32_e32 v200, v87, v87
	v_pk_add_f32 v[192:193], v[202:203], v[198:199]
	v_pk_add_f32 v[46:47], v[46:47], v[190:191]
	v_pk_fma_f32 v[196:197], v[84:85], v[84:85], v[100:101] op_sel_hi:[1,1,0]
	v_pk_fma_f32 v[200:201], v[86:87], v[86:87], v[200:201] op_sel_hi:[1,1,0]
	s_waitcnt vmcnt(9)
	v_mul_f32_e32 v189, v80, v80
	v_mul_f32_e32 v208, v81, v81
	v_pk_add_f32 v[190:191], v[192:193], v[192:193] op_sel:[0,1] op_sel_hi:[1,0]
	v_pk_add_f32 v[46:47], v[46:47], v[46:47] op_sel:[0,1] op_sel_hi:[1,0]
	v_mul_f32_e32 v197, v82, v82
	v_mul_f32_e32 v201, v83, v83
	s_waitcnt vmcnt(8)
	v_pk_mul_f32 v[194:195], v[78:79], v[78:79]
	v_pk_mul_f32 v[198:199], v[76:77], v[76:77]
	v_mov_b32_e32 v191, v208
	v_mov_b32_e32 v47, v189
	v_pk_mov_b32 v[192:193], v[198:199], v[194:195] op_sel:[1,0]
	v_mov_b32_e32 v199, v195
	v_pk_add_f32 v[196:197], v[196:197], v[200:201]
	v_pk_add_f32 v[46:47], v[46:47], v[190:191]
	s_waitcnt vmcnt(6)
	v_mul_f32_e32 v100, v73, v73
	v_mul_f32_e32 v202, v75, v75
	v_pk_add_f32 v[192:193], v[192:193], v[198:199]
	v_pk_add_f32 v[46:47], v[46:47], v[196:197]
	v_mul_f32_e32 v209, v68, v68
	v_mul_f32_e32 v212, v69, v69
	v_mul_f32_e32 v213, v70, v70
	v_mul_f32_e32 v214, v71, v71
	v_pk_fma_f32 v[194:195], v[72:73], v[72:73], v[100:101] op_sel_hi:[1,1,0]
	v_pk_fma_f32 v[202:203], v[74:75], v[74:75], v[202:203] op_sel_hi:[1,1,0]
	v_pk_add_f32 v[192:193], v[192:193], v[192:193] op_sel:[0,1] op_sel_hi:[1,0]
	v_pk_add_f32 v[46:47], v[46:47], v[46:47] op_sel:[0,1] op_sel_hi:[1,0]
	v_mov_b32_e32 v195, v213
	v_mov_b32_e32 v203, v214
	v_mov_b32_e32 v193, v212
	v_mov_b32_e32 v47, v209
	v_mov_b32_e32 v206, v65
	v_mov_b32_e32 v207, v61
	v_pk_add_f32 v[194:195], v[194:195], v[202:203]
	v_pk_add_f32 v[46:47], v[46:47], v[192:193]
	v_mov_b32_e32 v192, v67
	v_mov_b32_e32 v193, v63
	v_mov_b32_e32 v204, v64
	v_mov_b32_e32 v205, v60
	v_pk_mul_f32 v[206:207], v[206:207], v[206:207]
	v_pk_add_f32 v[46:47], v[46:47], v[194:195]
	v_mov_b32_e32 v190, v66
	v_mov_b32_e32 v191, v62
	v_pk_mul_f32 v[192:193], v[192:193], v[192:193]
	v_add_f32_e32 v189, v46, v47
	v_pk_fma_f32 v[46:47], v[204:205], v[204:205], v[206:207]
	v_pk_fma_f32 v[190:191], v[190:191], v[190:191], v[192:193]
	s_waitcnt vmcnt(5)
	v_pk_mul_f32 v[192:193], v[56:57], v[56:57]
	v_pk_add_f32 v[46:47], v[46:47], v[190:191]
	v_pk_mul_f32 v[190:191], v[58:59], v[58:59]
	s_waitcnt vmcnt(3)
	v_mul_f32_e32 v100, v48, v48
	v_pk_mov_b32 v[194:195], v[192:193], v[190:191] op_sel:[1,0]
	v_mov_b32_e32 v193, v191
	v_pk_add_f32 v[190:191], v[194:195], v[192:193]
	v_mul_f32_e32 v192, v49, v49
	v_pk_add_f32 v[46:47], v[46:47], v[46:47] op_sel:[0,1] op_sel_hi:[1,0]
	v_pk_add_f32 v[190:191], v[190:191], v[190:191] op_sel:[0,1] op_sel_hi:[1,0]
	v_mov_b32_e32 v47, v100
	v_mov_b32_e32 v191, v192
	v_mul_f32_e32 v100, v53, v53
	v_mul_f32_e32 v193, v50, v50
	v_pk_add_f32 v[46:47], v[46:47], v[190:191]
	v_pk_fma_f32 v[190:191], v[52:53], v[52:53], v[100:101] op_sel_hi:[1,1,0]
	v_mul_f32_e32 v100, v55, v55
	v_mov_b32_e32 v191, v193
	v_pk_fma_f32 v[192:193], v[54:55], v[54:55], v[100:101] op_sel_hi:[1,1,0]
	s_waitcnt lgkmcnt(0)
	s_nop 1
	v_add_f32_dpp v100, v189, v189 quad_perm:[1,0,3,2] row_mask:0xf bank_mask:0xf
	v_mul_f32_e32 v194, v51, v51
	v_mov_b32_e32 v193, v194
	v_pk_add_f32 v[190:191], v[190:191], v[192:193]
	s_waitcnt vmcnt(2)
	v_pk_mul_f32 v[192:193], v[42:43], v[42:43]
	s_waitcnt lgkmcnt(0)
	s_nop 1
	v_add_f32_dpp v100, v100, v100 quad_perm:[2,3,0,1] row_mask:0xf bank_mask:0xf
	v_pk_add_f32 v[46:47], v[46:47], v[190:191]
	v_pk_mul_f32 v[190:191], v[44:45], v[44:45]
	v_pk_add_f32 v[46:47], v[46:47], v[46:47] op_sel:[0,1] op_sel_hi:[1,0]
	v_pk_mov_b32 v[194:195], v[192:193], v[190:191] op_sel:[1,0]
	s_waitcnt lgkmcnt(0)
	s_nop 1
	v_add_f32_dpp v100, v100, v100 row_half_mirror row_mask:0xf bank_mask:0xf
	v_mov_b32_e32 v193, v191
	v_pk_add_f32 v[190:191], v[194:195], v[192:193]
	s_waitcnt vmcnt(0)
	v_mul_f32_e32 v192, v34, v34
	v_mov_b32_e32 v47, v192
	s_waitcnt lgkmcnt(0)
	s_nop 1
	v_add_f32_dpp v189, v100, v100 row_mirror row_mask:0xf bank_mask:0xf
	ds_bpermute_b32 v192, v155, v189
	v_mul_f32_e32 v193, v35, v35
	v_pk_add_f32 v[190:191], v[190:191], v[190:191] op_sel:[0,1] op_sel_hi:[1,0]
	v_mul_f32_e32 v100, v39, v39
	v_mov_b32_e32 v191, v193
	s_waitcnt lgkmcnt(0)
	v_add_f32_e32 v189, v189, v192
	ds_bpermute_b32 v196, v156, v189
	v_pk_add_f32 v[46:47], v[46:47], v[190:191]
	v_pk_fma_f32 v[190:191], v[38:39], v[38:39], v[100:101] op_sel_hi:[1,1,0]
	v_mul_f32_e32 v100, v41, v41
	v_pk_fma_f32 v[192:193], v[40:41], v[40:41], v[100:101] op_sel_hi:[1,1,0]
	s_waitcnt lgkmcnt(0)
	v_add_f32_e32 v100, v189, v196
	v_fmamk_f32 v100, v100, 0x3a000000, v182
	v_mul_f32_e32 v189, 0x4f800000, v100
	v_cmp_gt_f32_e32 vcc, s31, v100
	v_mul_f32_e32 v194, v36, v36
	v_mul_f32_e32 v195, v37, v37
	v_cndmask_b32_e32 v100, v100, v189, vcc
	v_sqrt_f32_e32 v189, v100
	v_mov_b32_e32 v191, v194
	v_mov_b32_e32 v193, v195
	v_pk_add_f32 v[190:191], v[190:191], v[192:193]
	s_nop 0
	v_pk_add_f32 v[46:47], v[46:47], v[190:191]
	v_add_u32_e32 v190, -1, v189
	v_fma_f32 v191, -v190, v189, v100
	v_cmp_ge_f32_e64 s[10:11], 0, v191
	v_add_u32_e32 v191, 1, v189
	v_add_f32_e32 v194, v46, v47
	v_cndmask_b32_e64 v190, v189, v190, s[10:11]
	v_fma_f32 v189, -v191, v189, v100
	v_cmp_lt_f32_e64 s[10:11], 0, v189
	s_nop 1
	v_cndmask_b32_e64 v189, v190, v191, s[10:11]
	v_mul_f32_e32 v190, 0x37800000, v189
	v_cndmask_b32_e32 v189, v189, v190, vcc
	v_cmp_class_f32_e32 vcc, v100, v183
	s_nop 1
	v_cndmask_b32_e32 v100, v189, v100, vcc
	v_div_scale_f32 v189, s[10:11], v100, v100, 1.0
	v_rcp_f32_e32 v190, v189
	s_add_i32 s10, s35, s14
	s_ashr_i32 s11, s10, 31
	s_lshl_b64 s[10:11], s[10:11], 11
	v_fma_f32 v46, -v189, v190, 1.0
	v_fmac_f32_e32 v190, v46, v190
	v_div_scale_f32 v46, vcc, 1.0, v100, 1.0
	v_mul_f32_e32 v47, v46, v190
	v_fma_f32 v191, -v189, v47, v46
	v_fmac_f32_e32 v47, v191, v190
	v_fma_f32 v46, -v189, v47, v46
	v_div_fmas_f32 v46, v46, v190, v47
	v_div_fixup_f32 v100, v46, v100, 1.0
	v_pk_mul_f32 v[46:47], v[96:97], v[100:101] op_sel_hi:[1,0]
	v_mov_b32_e32 v189, v101
	v_pk_fma_f32 v[190:191], v[120:121], v[46:47], v[2:3]
	v_pk_mul_f32 v[46:47], v[98:99], v[100:101] op_sel_hi:[1,0]
	v_cvt_pk_fp8_f32 v189, v190, v191
	v_pk_fma_f32 v[98:99], v[118:119], v[46:47], v[4:5]
	v_lshl_add_u64 v[96:97], v[116:117], 0, s[10:11]
	v_pk_mul_f32 v[92:93], v[92:93], v[100:101] op_sel_hi:[1,0]
	v_cvt_pk_fp8_f32 v189, v98, v99 op_sel:[0,0,1]
	v_pk_fma_f32 v[92:93], v[124:125], v[92:93], v[6:7]
	v_pk_mul_f32 v[94:95], v[94:95], v[100:101] op_sel_hi:[1,0]
	v_pk_mul_f32 v[88:89], v[88:89], v[100:101] op_sel_hi:[1,0]
	global_store_dword v[96:97], v189, off
	v_cvt_pk_bf16_f32 v192, v190, v191
	v_cvt_pk_bf16_f32 v193, v98, v99
	v_pk_fma_f32 v[94:95], v[122:123], v[94:95], v[8:9]
	v_lshlrev_b32_e32 v47, 16, v192
	v_sub_f32_e32 v47, v190, v47
	v_and_b32_e32 v189, 0xffff0000, v192
	v_sub_f32_e32 v189, v191, v189
	v_cvt_pk_bf16_f32 v190, v47, v189
	v_lshlrev_b32_e32 v47, 16, v193
	v_sub_f32_e32 v47, v98, v47
	v_and_b32_e32 v98, 0xffff0000, v193
	v_sub_f32_e32 v98, v99, v98
	v_cvt_pk_bf16_f32 v191, v47, v98
	v_mov_b32_e32 v47, v101
	v_cvt_pk_fp8_f32 v47, v92, v93
	v_add_u32_e32 v98, s15, v163
	ds_write_b64 v98, v[192:193]
	v_add_u32_e32 v98, s26, v163
	v_cvt_pk_fp8_f32 v47, v94, v95 op_sel:[0,0,1]
	ds_write_b64 v98, v[190:191]
	v_pk_fma_f32 v[88:89], v[128:129], v[88:89], v[10:11]
	v_pk_mul_f32 v[90:91], v[90:91], v[100:101] op_sel_hi:[1,0]
	global_store_dword v[96:97], v47, off offset:256
	v_cvt_pk_bf16_f32 v98, v92, v93
	v_cvt_pk_bf16_f32 v99, v94, v95
	v_pk_fma_f32 v[90:91], v[126:127], v[90:91], v[12:13]
	v_lshlrev_b32_e32 v47, 16, v98
	v_sub_f32_e32 v47, v92, v47
	v_and_b32_e32 v92, 0xffff0000, v98
	v_sub_f32_e32 v92, v93, v92
	v_cvt_pk_bf16_f32 v92, v47, v92
	v_lshlrev_b32_e32 v47, 16, v99
	v_and_b32_e32 v93, 0xffff0000, v99
	v_sub_f32_e32 v47, v94, v47
	v_sub_f32_e32 v93, v95, v93
	v_cvt_pk_bf16_f32 v93, v47, v93
	v_mov_b32_e32 v47, v101
	v_cvt_pk_fp8_f32 v47, v88, v89
	v_add_u32_e32 v94, s15, v164
	ds_write_b64 v94, v[98:99]
	v_add_u32_e32 v94, s26, v164
	v_cvt_pk_fp8_f32 v47, v90, v91 op_sel:[0,0,1]
	ds_write_b64 v94, v[92:93]
	v_pk_mul_f32 v[84:85], v[84:85], v[100:101] op_sel_hi:[1,0]
	v_pk_mul_f32 v[86:87], v[86:87], v[100:101] op_sel_hi:[1,0]
	global_store_dword v[96:97], v47, off offset:512
	v_cvt_pk_bf16_f32 v92, v88, v89
	v_cvt_pk_bf16_f32 v93, v90, v91
	v_pk_fma_f32 v[84:85], v[132:133], v[84:85], v[14:15]
	v_lshlrev_b32_e32 v47, 16, v92
	v_sub_f32_e32 v47, v88, v47
	v_and_b32_e32 v88, 0xffff0000, v92
	v_sub_f32_e32 v88, v89, v88
	v_cvt_pk_bf16_f32 v88, v47, v88
	v_lshlrev_b32_e32 v47, 16, v93
	v_and_b32_e32 v89, 0xffff0000, v93
	v_sub_f32_e32 v47, v90, v47
	v_sub_f32_e32 v89, v91, v89
	v_cvt_pk_bf16_f32 v89, v47, v89
	v_mov_b32_e32 v47, v101
	v_cvt_pk_fp8_f32 v47, v84, v85
	v_pk_fma_f32 v[86:87], v[130:131], v[86:87], v[16:17]
	v_add_u32_e32 v90, s15, v165
	ds_write_b64 v90, v[92:93]
	v_cvt_pk_fp8_f32 v47, v86, v87 op_sel:[0,0,1]
	v_add_u32_e32 v90, s26, v165
	ds_write_b64 v90, v[88:89]
	v_pk_mul_f32 v[80:81], v[80:81], v[100:101] op_sel_hi:[1,0]
	global_store_dword v[96:97], v47, off offset:768
	v_cvt_pk_bf16_f32 v88, v84, v85
	v_cvt_pk_bf16_f32 v89, v86, v87
	v_pk_fma_f32 v[80:81], v[136:137], v[80:81], v[18:19]
	v_lshlrev_b32_e32 v47, 16, v88
	v_sub_f32_e32 v47, v84, v47
	v_and_b32_e32 v84, 0xffff0000, v88
	v_sub_f32_e32 v84, v85, v84
	v_cvt_pk_bf16_f32 v84, v47, v84
	v_lshlrev_b32_e32 v47, 16, v89
	v_and_b32_e32 v85, 0xffff0000, v89
	v_sub_f32_e32 v47, v86, v47
	v_sub_f32_e32 v85, v87, v85
	v_cvt_pk_bf16_f32 v85, v47, v85
	v_mov_b32_e32 v47, v101
	v_cvt_pk_fp8_f32 v47, v80, v81
	v_pk_mul_f32 v[82:83], v[82:83], v[100:101] op_sel_hi:[1,0]
	v_add_u32_e32 v86, s15, v166
	v_pk_fma_f32 v[82:83], v[134:135], v[82:83], v[20:21]
	ds_write_b64 v86, v[88:89]
	v_cvt_pk_fp8_f32 v47, v82, v83 op_sel:[0,0,1]
	v_add_u32_e32 v86, s26, v166
	ds_write_b64 v86, v[84:85]
	v_pk_mul_f32 v[76:77], v[76:77], v[100:101] op_sel_hi:[1,0]
	global_store_dword v[96:97], v47, off offset:1024
	v_cvt_pk_bf16_f32 v84, v80, v81
	v_cvt_pk_bf16_f32 v85, v82, v83
	v_pk_fma_f32 v[76:77], v[140:141], v[76:77], v[22:23]
	v_lshlrev_b32_e32 v47, 16, v84
	v_sub_f32_e32 v47, v80, v47
	v_and_b32_e32 v80, 0xffff0000, v84
	v_sub_f32_e32 v80, v81, v80
	v_cvt_pk_bf16_f32 v80, v47, v80
	v_lshlrev_b32_e32 v47, 16, v85
	v_and_b32_e32 v81, 0xffff0000, v85
	v_sub_f32_e32 v47, v82, v47
	v_sub_f32_e32 v81, v83, v81
	v_cvt_pk_bf16_f32 v81, v47, v81
	v_mov_b32_e32 v47, v101
	v_cvt_pk_fp8_f32 v47, v76, v77
	v_pk_mul_f32 v[78:79], v[78:79], v[100:101] op_sel_hi:[1,0]
	v_add_u32_e32 v82, s15, v167
	v_pk_fma_f32 v[78:79], v[138:139], v[78:79], v[24:25]
	ds_write_b64 v82, v[84:85]
	v_cvt_pk_fp8_f32 v47, v78, v79 op_sel:[0,0,1]
	v_add_u32_e32 v82, s26, v167
	ds_write_b64 v82, v[80:81]
	v_pk_mul_f32 v[72:73], v[72:73], v[100:101] op_sel_hi:[1,0]
	global_store_dword v[96:97], v47, off offset:1280
	v_cvt_pk_bf16_f32 v80, v76, v77
	v_cvt_pk_bf16_f32 v81, v78, v79
	v_pk_fma_f32 v[72:73], v[144:145], v[72:73], v[26:27]
	v_lshlrev_b32_e32 v47, 16, v80
	v_sub_f32_e32 v47, v76, v47
	v_and_b32_e32 v76, 0xffff0000, v80
	v_sub_f32_e32 v76, v77, v76
	v_cvt_pk_bf16_f32 v76, v47, v76
	v_lshlrev_b32_e32 v47, 16, v81
	v_and_b32_e32 v77, 0xffff0000, v81
	v_sub_f32_e32 v47, v78, v47
	v_sub_f32_e32 v77, v79, v77
	v_cvt_pk_bf16_f32 v77, v47, v77
	v_mov_b32_e32 v47, v101
	v_cvt_pk_fp8_f32 v47, v72, v73
	v_pk_mul_f32 v[74:75], v[74:75], v[100:101] op_sel_hi:[1,0]
	v_add_u32_e32 v78, s15, v168
	v_pk_fma_f32 v[74:75], v[142:143], v[74:75], v[28:29]
	ds_write_b64 v78, v[80:81]
	v_cvt_pk_fp8_f32 v47, v74, v75 op_sel:[0,0,1]
	v_add_u32_e32 v78, s26, v168
	ds_write_b64 v78, v[76:77]
	v_pk_mul_f32 v[68:69], v[68:69], v[100:101] op_sel_hi:[1,0]
	global_store_dword v[96:97], v47, off offset:1536
	v_cvt_pk_bf16_f32 v76, v72, v73
	v_cvt_pk_bf16_f32 v77, v74, v75
	v_pk_fma_f32 v[68:69], v[148:149], v[68:69], v[30:31]
	v_lshlrev_b32_e32 v47, 16, v76
	v_sub_f32_e32 v47, v72, v47
	v_and_b32_e32 v72, 0xffff0000, v76
	v_sub_f32_e32 v72, v73, v72
	v_cvt_pk_bf16_f32 v72, v47, v72
	v_lshlrev_b32_e32 v47, 16, v77
	v_sub_f32_e32 v47, v74, v47
	v_and_b32_e32 v73, 0xffff0000, v77
	v_sub_f32_e32 v73, v75, v73
	v_cvt_pk_bf16_f32 v73, v47, v73
	v_add_u32_e32 v47, s15, v169
	ds_write_b64 v47, v[76:77]
	s_waitcnt lgkmcnt(1)
	s_nop 1
	v_add_f32_dpp v47, v194, v194 quad_perm:[1,0,3,2] row_mask:0xf bank_mask:0xf
	v_mov_b32_e32 v75, v101
	v_cvt_pk_fp8_f32 v75, v68, v69
	v_pk_mul_f32 v[70:71], v[70:71], v[100:101] op_sel_hi:[1,0]
	v_add_u32_e32 v76, s26, v169
	s_waitcnt lgkmcnt(0)
	s_nop 1
	v_add_f32_dpp v47, v47, v47 quad_perm:[2,3,0,1] row_mask:0xf bank_mask:0xf
	v_pk_fma_f32 v[70:71], v[146:147], v[70:71], v[32:33]
	ds_write_b64 v76, v[72:73]
	v_cvt_pk_fp8_f32 v75, v70, v71 op_sel:[0,0,1]
	v_mov_b32_e32 v46, 0
	s_waitcnt lgkmcnt(1)
	s_nop 1
	v_add_f32_dpp v47, v47, v47 row_half_mirror row_mask:0xf bank_mask:0xf
	global_store_dword v[96:97], v75, off offset:1792
	v_cvt_pk_bf16_f32 v72, v68, v69
	v_cvt_pk_bf16_f32 v73, v70, v71
	s_waitcnt lgkmcnt(0)
	s_nop 1
	v_add_f32_dpp v47, v47, v47 row_mirror row_mask:0xf bank_mask:0xf
	ds_bpermute_b32 v74, v155, v47
	v_lshlrev_b32_e32 v75, 16, v72
	v_sub_f32_e32 v68, v68, v75
	v_and_b32_e32 v75, 0xffff0000, v72
	v_sub_f32_e32 v69, v69, v75
	s_waitcnt lgkmcnt(0)
	v_add_f32_e32 v47, v47, v74
	ds_bpermute_b32 v74, v156, v47
	v_cvt_pk_bf16_f32 v68, v68, v69
	v_lshlrev_b32_e32 v69, 16, v73
	v_sub_f32_e32 v69, v70, v69
	v_and_b32_e32 v70, 0xffff0000, v73
	s_waitcnt lgkmcnt(0)
	v_add_f32_e32 v47, v47, v74
	v_fmamk_f32 v47, v47, 0x3a000000, v182
	v_mul_f32_e32 v74, 0x4f800000, v47
	v_cmp_gt_f32_e32 vcc, s31, v47
	v_sub_f32_e32 v70, v71, v70
	v_cvt_pk_bf16_f32 v69, v69, v70
	v_add_u32_e32 v70, s15, v170
	v_cndmask_b32_e32 v47, v47, v74, vcc
	v_sqrt_f32_e32 v74, v47
	ds_write_b64 v70, v[72:73]
	v_add_u32_e32 v70, s26, v170
	ds_write_b64 v70, v[68:69]
	v_add_u32_e32 v71, -1, v74
	v_fma_f32 v75, -v71, v74, v47
	v_cmp_ge_f32_e64 s[10:11], 0, v75
	v_add_u32_e32 v75, 1, v74
	s_nop 0
	v_cndmask_b32_e64 v71, v74, v71, s[10:11]
	v_fma_f32 v74, -v75, v74, v47
	v_cmp_lt_f32_e64 s[10:11], 0, v74
	s_nop 1
	v_cndmask_b32_e64 v71, v71, v75, s[10:11]
	v_mul_f32_e32 v74, 0x37800000, v71
	v_cndmask_b32_e32 v71, v71, v74, vcc
	v_cmp_class_f32_e32 vcc, v47, v183
	s_nop 1
	v_cndmask_b32_e32 v47, v71, v47, vcc
	v_div_scale_f32 v71, s[10:11], v47, v47, 1.0
	v_rcp_f32_e32 v74, v71
	s_add_i32 s10, s35, s27
	s_ashr_i32 s11, s10, 31
	s_lshl_b64 s[10:11], s[10:11], 11
	v_fma_f32 v68, -v71, v74, 1.0
	v_fmac_f32_e32 v74, v68, v74
	v_div_scale_f32 v68, vcc, 1.0, v47, 1.0
	v_mul_f32_e32 v69, v68, v74
	v_fma_f32 v70, -v71, v69, v68
	v_fmac_f32_e32 v69, v70, v74
	v_fma_f32 v68, -v71, v69, v68
	v_div_fmas_f32 v68, v68, v74, v69
	v_div_fixup_f32 v68, v68, v47, 1.0
	v_pk_mul_f32 v[64:65], v[64:65], v[68:69] op_sel_hi:[1,0]
	v_mov_b32_e32 v47, v101
	v_pk_fma_f32 v[70:71], v[120:121], v[64:65], v[2:3]
	v_pk_mul_f32 v[64:65], v[66:67], v[68:69] op_sel_hi:[1,0]
	v_cvt_pk_fp8_f32 v47, v70, v71
	v_pk_fma_f32 v[66:67], v[118:119], v[64:65], v[4:5]
	v_lshl_add_u64 v[64:65], v[116:117], 0, s[10:11]
	s_mov_b64 s[10:11], -1
	v_cvt_pk_fp8_f32 v47, v66, v67 op_sel:[0,0,1]
	global_store_dword v[64:65], v47, off
	v_cvt_pk_bf16_f32 v72, v70, v71
	v_cvt_pk_bf16_f32 v73, v66, v67
	s_nop 0
	v_lshlrev_b32_e32 v47, 16, v72
	v_sub_f32_e32 v47, v70, v47
	v_and_b32_e32 v69, 0xffff0000, v72
	v_sub_f32_e32 v69, v71, v69
	v_cvt_pk_bf16_f32 v70, v47, v69
	v_lshlrev_b32_e32 v47, 16, v73
	v_sub_f32_e32 v47, v66, v47
	v_and_b32_e32 v66, 0xffff0000, v73
	v_pk_mul_f32 v[60:61], v[60:61], v[68:69] op_sel_hi:[1,0]
	v_sub_f32_e32 v66, v67, v66
	v_cvt_pk_bf16_f32 v71, v47, v66
	v_pk_fma_f32 v[60:61], v[124:125], v[60:61], v[6:7]
	v_mov_b32_e32 v47, v101
	v_cvt_pk_fp8_f32 v47, v60, v61
	v_pk_mul_f32 v[62:63], v[62:63], v[68:69] op_sel_hi:[1,0]
	v_add_u32_e32 v66, s28, v163
	v_pk_fma_f32 v[62:63], v[122:123], v[62:63], v[8:9]
	ds_write_b64 v66, v[72:73]
	v_cvt_pk_fp8_f32 v47, v62, v63 op_sel:[0,0,1]
	v_add_u32_e32 v66, s29, v163
	ds_write_b64 v66, v[70:71]
	v_pk_mul_f32 v[56:57], v[56:57], v[68:69] op_sel_hi:[1,0]
	global_store_dword v[64:65], v47, off offset:256
	v_cvt_pk_bf16_f32 v66, v60, v61
	v_cvt_pk_bf16_f32 v67, v62, v63
	v_pk_fma_f32 v[56:57], v[128:129], v[56:57], v[10:11]
	v_lshlrev_b32_e32 v47, 16, v66
	v_sub_f32_e32 v47, v60, v47
	v_and_b32_e32 v60, 0xffff0000, v66
	v_sub_f32_e32 v60, v61, v60
	v_cvt_pk_bf16_f32 v60, v47, v60
	v_lshlrev_b32_e32 v47, 16, v67
	v_and_b32_e32 v61, 0xffff0000, v67
	v_sub_f32_e32 v47, v62, v47
	v_sub_f32_e32 v61, v63, v61
	v_cvt_pk_bf16_f32 v61, v47, v61
	v_mov_b32_e32 v47, v101
	v_cvt_pk_fp8_f32 v47, v56, v57
	v_pk_mul_f32 v[58:59], v[58:59], v[68:69] op_sel_hi:[1,0]
	v_add_u32_e32 v62, s28, v164
	v_pk_fma_f32 v[58:59], v[126:127], v[58:59], v[12:13]
	ds_write_b64 v62, v[66:67]
	v_cvt_pk_fp8_f32 v47, v58, v59 op_sel:[0,0,1]
	v_add_u32_e32 v62, s29, v164
	ds_write_b64 v62, v[60:61]
	v_pk_mul_f32 v[52:53], v[52:53], v[68:69] op_sel_hi:[1,0]
	global_store_dword v[64:65], v47, off offset:512
	v_cvt_pk_bf16_f32 v60, v56, v57
	v_cvt_pk_bf16_f32 v61, v58, v59
	v_pk_fma_f32 v[52:53], v[132:133], v[52:53], v[14:15]
	v_lshlrev_b32_e32 v47, 16, v60
	v_sub_f32_e32 v47, v56, v47
	v_and_b32_e32 v56, 0xffff0000, v60
	v_sub_f32_e32 v56, v57, v56
	v_cvt_pk_bf16_f32 v56, v47, v56
	v_lshlrev_b32_e32 v47, 16, v61
	v_and_b32_e32 v57, 0xffff0000, v61
	v_sub_f32_e32 v47, v58, v47
	v_sub_f32_e32 v57, v59, v57
	v_cvt_pk_bf16_f32 v57, v47, v57
	v_mov_b32_e32 v47, v101
	v_cvt_pk_fp8_f32 v47, v52, v53
	v_pk_mul_f32 v[54:55], v[54:55], v[68:69] op_sel_hi:[1,0]
	v_add_u32_e32 v58, s28, v165
	v_pk_fma_f32 v[54:55], v[130:131], v[54:55], v[16:17]
	ds_write_b64 v58, v[60:61]
	v_cvt_pk_fp8_f32 v47, v54, v55 op_sel:[0,0,1]
	v_add_u32_e32 v58, s29, v165
	ds_write_b64 v58, v[56:57]
	v_pk_mul_f32 v[48:49], v[48:49], v[68:69] op_sel_hi:[1,0]
	global_store_dword v[64:65], v47, off offset:768
	v_cvt_pk_bf16_f32 v56, v52, v53
	v_cvt_pk_bf16_f32 v57, v54, v55
	v_pk_fma_f32 v[48:49], v[136:137], v[48:49], v[18:19]
	v_lshlrev_b32_e32 v47, 16, v56
	v_sub_f32_e32 v47, v52, v47
	v_and_b32_e32 v52, 0xffff0000, v56
	v_sub_f32_e32 v52, v53, v52
	v_cvt_pk_bf16_f32 v52, v47, v52
	v_lshlrev_b32_e32 v47, 16, v57
	v_and_b32_e32 v53, 0xffff0000, v57
	v_sub_f32_e32 v47, v54, v47
	v_sub_f32_e32 v53, v55, v53
	v_cvt_pk_bf16_f32 v53, v47, v53
	v_mov_b32_e32 v47, v101
	v_cvt_pk_fp8_f32 v47, v48, v49
	v_pk_mul_f32 v[50:51], v[50:51], v[68:69] op_sel_hi:[1,0]
	v_add_u32_e32 v54, s28, v166
	v_pk_fma_f32 v[50:51], v[134:135], v[50:51], v[20:21]
	ds_write_b64 v54, v[56:57]
	v_cvt_pk_fp8_f32 v47, v50, v51 op_sel:[0,0,1]
	v_add_u32_e32 v54, s29, v166
	ds_write_b64 v54, v[52:53]
	v_pk_mul_f32 v[42:43], v[42:43], v[68:69] op_sel_hi:[1,0]
	global_store_dword v[64:65], v47, off offset:1024
	v_cvt_pk_bf16_f32 v52, v48, v49
	v_cvt_pk_bf16_f32 v53, v50, v51
	v_pk_fma_f32 v[42:43], v[140:141], v[42:43], v[22:23]
	v_lshlrev_b32_e32 v47, 16, v52
	v_sub_f32_e32 v47, v48, v47
	v_and_b32_e32 v48, 0xffff0000, v52
	v_sub_f32_e32 v48, v49, v48
	v_cvt_pk_bf16_f32 v48, v47, v48
	v_lshlrev_b32_e32 v47, 16, v53
	v_and_b32_e32 v49, 0xffff0000, v53
	v_sub_f32_e32 v47, v50, v47
	v_sub_f32_e32 v49, v51, v49
	v_cvt_pk_bf16_f32 v49, v47, v49
	v_mov_b32_e32 v47, v101
	v_cvt_pk_fp8_f32 v47, v42, v43
	v_pk_mul_f32 v[44:45], v[44:45], v[68:69] op_sel_hi:[1,0]
	v_add_u32_e32 v50, s28, v167
	v_pk_fma_f32 v[44:45], v[138:139], v[44:45], v[24:25]
	ds_write_b64 v50, v[52:53]
	v_cvt_pk_fp8_f32 v47, v44, v45 op_sel:[0,0,1]
	v_add_u32_e32 v50, s29, v167
	ds_write_b64 v50, v[48:49]
	v_pk_mul_f32 v[38:39], v[38:39], v[68:69] op_sel_hi:[1,0]
	global_store_dword v[64:65], v47, off offset:1280
	v_cvt_pk_bf16_f32 v48, v42, v43
	v_cvt_pk_bf16_f32 v49, v44, v45
	v_pk_fma_f32 v[38:39], v[144:145], v[38:39], v[26:27]
	v_lshlrev_b32_e32 v47, 16, v48
	v_sub_f32_e32 v42, v42, v47
	v_and_b32_e32 v47, 0xffff0000, v48
	v_sub_f32_e32 v43, v43, v47
	v_cvt_pk_bf16_f32 v42, v42, v43
	v_lshlrev_b32_e32 v43, 16, v49
	v_sub_f32_e32 v43, v44, v43
	v_and_b32_e32 v44, 0xffff0000, v49
	v_sub_f32_e32 v44, v45, v44
	v_cvt_pk_bf16_f32 v43, v43, v44
	v_mov_b32_e32 v44, v101
	v_cvt_pk_fp8_f32 v44, v38, v39
	v_pk_mul_f32 v[40:41], v[40:41], v[68:69] op_sel_hi:[1,0]
	v_add_u32_e32 v45, s28, v168
	v_pk_fma_f32 v[40:41], v[142:143], v[40:41], v[28:29]
	ds_write_b64 v45, v[48:49]
	v_cvt_pk_fp8_f32 v44, v40, v41 op_sel:[0,0,1]
	v_add_u32_e32 v45, s29, v168
	ds_write_b64 v45, v[42:43]
	v_pk_mul_f32 v[34:35], v[34:35], v[68:69] op_sel_hi:[1,0]
	global_store_dword v[64:65], v44, off offset:1536
	v_cvt_pk_bf16_f32 v42, v38, v39
	v_cvt_pk_bf16_f32 v43, v40, v41
	v_pk_fma_f32 v[34:35], v[148:149], v[34:35], v[30:31]
	v_lshlrev_b32_e32 v44, 16, v42
	v_sub_f32_e32 v38, v38, v44
	v_and_b32_e32 v44, 0xffff0000, v42
	v_sub_f32_e32 v39, v39, v44
	v_cvt_pk_bf16_f32 v38, v38, v39
	v_lshlrev_b32_e32 v39, 16, v43
	v_sub_f32_e32 v39, v40, v39
	v_and_b32_e32 v40, 0xffff0000, v43
	v_sub_f32_e32 v40, v41, v40
	v_cvt_pk_bf16_f32 v39, v39, v40
	v_mov_b32_e32 v40, v101
	v_cvt_pk_fp8_f32 v40, v34, v35
	v_pk_mul_f32 v[36:37], v[36:37], v[68:69] op_sel_hi:[1,0]
	v_add_u32_e32 v41, s28, v169
	v_pk_fma_f32 v[36:37], v[146:147], v[36:37], v[32:33]
	ds_write_b64 v41, v[42:43]
	v_cvt_pk_fp8_f32 v40, v36, v37 op_sel:[0,0,1]
	v_add_u32_e32 v41, s29, v169
	ds_write_b64 v41, v[38:39]
	v_mov_b32_e32 v47, v46
	global_store_dword v[64:65], v40, off offset:1792
	v_cvt_pk_bf16_f32 v38, v34, v35
	v_cvt_pk_bf16_f32 v39, v36, v37
	v_mov_b32_e32 v48, v46
	v_lshlrev_b32_e32 v40, 16, v38
	v_sub_f32_e32 v34, v34, v40
	v_and_b32_e32 v40, 0xffff0000, v38
	v_sub_f32_e32 v35, v35, v40
	v_cvt_pk_bf16_f32 v34, v34, v35
	v_lshlrev_b32_e32 v35, 16, v39
	v_sub_f32_e32 v35, v36, v35
	v_and_b32_e32 v36, 0xffff0000, v39
	v_sub_f32_e32 v36, v37, v36
	v_cvt_pk_bf16_f32 v35, v35, v36
	v_add_u32_e32 v36, s28, v170
	ds_write_b64 v36, v[38:39]
	v_add_u32_e32 v36, s29, v170
	ds_write_b64 v36, v[34:35]
	s_waitcnt lgkmcnt(0)
	s_barrier
	v_mov_b32_e32 v49, v46
	v_mov_b32_e32 v34, v46
	v_mov_b32_e32 v35, v46
	v_mov_b32_e32 v36, v46
	v_mov_b32_e32 v37, v46
.LBB0_1158:
	v_lshl_or_b32 v38, s2, 7, v158
	v_add_u32_e32 v100, v38, v157
	v_lshlrev_b64 v[74:75], 1, v[100:101]
	v_add_u32_e32 v100, v38, v171
	v_lshl_or_b32 v39, s2, 8, v159
	v_lshlrev_b64 v[82:83], 1, v[100:101]
	v_add_u32_e32 v62, v160, v39
	v_add_u32_e32 v70, v161, v39
	v_lshl_add_u64 v[76:77], s[16:17], 0, v[74:75]
	v_lshl_add_u64 v[78:79], s[18:19], 0, v[74:75]
	v_lshl_add_u64 v[84:85], s[16:17], 0, v[82:83]
	v_or_b32_e32 v92, 32, v38
	v_or_b32_e32 v93, 64, v38
	v_or_b32_e32 v94, 0x60, v38
	ds_read_b128 v[38:41], v62
	ds_read_b128 v[42:45], v62 offset:64
	ds_read_b128 v[50:53], v70
	ds_read_b128 v[54:57], v70 offset:64
	ds_read_b128 v[58:61], v62 offset:128
	ds_read_b128 v[62:65], v62 offset:192
	ds_read_b128 v[66:69], v70 offset:128
	ds_read_b128 v[70:73], v70 offset:192
	global_load_dwordx4 v[74:77], v[76:77], off
	s_nop 0
	global_load_dwordx4 v[78:81], v[78:79], off
	v_lshl_add_u64 v[86:87], s[18:19], 0, v[82:83]
	global_load_dwordx4 v[82:85], v[84:85], off
	v_add_u32_e32 v100, v92, v157
	global_load_dwordx4 v[86:89], v[86:87], off
	v_lshlrev_b64 v[90:91], 1, v[100:101]
	v_add_u32_e32 v100, v92, v171
	s_mov_b32 s2, 1
	s_waitcnt vmcnt(3) lgkmcnt(7)
	v_mfma_f32_16x16x32_bf16 v[46:49], v[38:41], v[74:77], v[46:49]
	s_waitcnt vmcnt(1)
	v_mfma_f32_16x16x32_bf16 v[34:37], v[38:41], v[82:85], v[34:37]
	v_mfma_f32_16x16x32_bf16 v[46:49], v[38:41], v[78:81], v[46:49]
	v_lshl_add_u64 v[78:79], s[16:17], 0, v[90:91]
	v_lshl_add_u64 v[80:81], s[18:19], 0, v[90:91]
	v_lshlrev_b64 v[90:91], 1, v[100:101]
	s_waitcnt vmcnt(0)
	v_mfma_f32_16x16x32_bf16 v[34:37], v[38:41], v[86:89], v[34:37]
	global_load_dwordx4 v[38:41], v[78:79], off
	v_add_u32_e32 v100, v93, v157
	s_waitcnt lgkmcnt(5)
	v_mfma_f32_16x16x32_bf16 v[46:49], v[50:53], v[74:77], v[46:49]
	global_load_dwordx4 v[74:77], v[80:81], off
	v_lshl_add_u64 v[78:79], s[16:17], 0, v[90:91]
	v_lshl_add_u64 v[80:81], s[18:19], 0, v[90:91]
	v_mfma_f32_16x16x32_bf16 v[34:37], v[50:53], v[82:85], v[34:37]
	global_load_dwordx4 v[50:53], v[78:79], off
	v_lshlrev_b64 v[82:83], 1, v[100:101]
	global_load_dwordx4 v[78:81], v[80:81], off
	v_add_u32_e32 v100, v93, v171
	s_waitcnt vmcnt(3)
	v_mfma_f32_16x16x32_bf16 v[46:49], v[42:45], v[38:41], v[46:49]
	s_waitcnt vmcnt(1)
	v_mfma_f32_16x16x32_bf16 v[34:37], v[42:45], v[50:53], v[34:37]
	v_mfma_f32_16x16x32_bf16 v[46:49], v[42:45], v[74:77], v[46:49]
	v_lshl_add_u64 v[74:75], s[16:17], 0, v[82:83]
	v_lshl_add_u64 v[76:77], s[18:19], 0, v[82:83]
	v_lshlrev_b64 v[82:83], 1, v[100:101]
	s_waitcnt vmcnt(0)
	v_mfma_f32_16x16x32_bf16 v[34:37], v[42:45], v[78:81], v[34:37]
	global_load_dwordx4 v[42:45], v[74:75], off
	v_add_u32_e32 v100, v94, v157
	s_waitcnt lgkmcnt(4)
	v_mfma_f32_16x16x32_bf16 v[38:41], v[54:57], v[38:41], v[46:49]
	s_nop 2
	global_load_dwordx4 v[46:49], v[76:77], off
	v_lshl_add_u64 v[74:75], s[16:17], 0, v[82:83]
	v_mfma_f32_16x16x32_bf16 v[34:37], v[54:57], v[50:53], v[34:37]
	global_load_dwordx4 v[50:53], v[74:75], off
	v_lshl_add_u64 v[76:77], s[18:19], 0, v[82:83]
	global_load_dwordx4 v[54:57], v[76:77], off
	v_lshlrev_b64 v[74:75], 1, v[100:101]
	v_add_u32_e32 v100, v94, v171
	v_lshlrev_b64 v[76:77], 1, v[100:101]
	s_waitcnt vmcnt(3) lgkmcnt(3)
	v_mfma_f32_16x16x32_bf16 v[38:41], v[58:61], v[42:45], v[38:41]
	s_waitcnt vmcnt(1)
	v_mfma_f32_16x16x32_bf16 v[34:37], v[58:61], v[50:53], v[34:37]
	s_waitcnt vmcnt(0)
	v_mfma_f32_16x16x32_bf16 v[34:37], v[58:61], v[54:57], v[34:37]
	v_lshl_add_u64 v[54:55], s[16:17], 0, v[76:77]
	v_lshl_add_u64 v[56:57], s[18:19], 0, v[76:77]
	v_mfma_f32_16x16x32_bf16 v[38:41], v[58:61], v[46:49], v[38:41]
	v_lshl_add_u64 v[46:47], s[16:17], 0, v[74:75]
	global_load_dwordx4 v[46:49], v[46:47], off
	v_lshl_add_u64 v[74:75], s[18:19], 0, v[74:75]
	s_waitcnt lgkmcnt(1)
	v_mfma_f32_16x16x32_bf16 v[34:37], v[66:69], v[50:53], v[34:37]
	global_load_dwordx4 v[50:53], v[54:55], off
	s_nop 0
	global_load_dwordx4 v[54:57], v[56:57], off
	v_mfma_f32_16x16x32_bf16 v[38:41], v[66:69], v[42:45], v[38:41]
	global_load_dwordx4 v[42:45], v[74:75], off
	s_waitcnt vmcnt(3)
	v_mfma_f32_16x16x32_bf16 v[38:41], v[62:65], v[46:49], v[38:41]
	s_waitcnt vmcnt(2)
	v_mfma_f32_16x16x32_bf16 v[34:37], v[62:65], v[50:53], v[34:37]
	s_waitcnt vmcnt(0)
	v_mfma_f32_16x16x32_bf16 v[38:41], v[62:65], v[42:45], v[38:41]
	v_mfma_f32_16x16x32_bf16 v[34:37], v[62:65], v[54:57], v[34:37]
	s_waitcnt lgkmcnt(0)
	v_mfma_f32_16x16x32_bf16 v[46:49], v[70:73], v[46:49], v[38:41]
	v_mfma_f32_16x16x32_bf16 v[34:37], v[70:73], v[50:53], v[34:37]
	s_nop 3
	v_cndmask_b32_e64 v38, 0, 1, s[10:11]
	v_cmp_ne_u32_e32 vcc, 1, v38
	s_mov_b64 s[10:11], 0
	s_cbranch_vccz .LBB0_1158
	s_waitcnt lgkmcnt(0)
	s_barrier
	ds_write2_b32 v184, v46, v34 offset1:16
	ds_write2_b32 v184, v47, v35 offset0:32 offset1:48
	ds_write2_b32 v184, v48, v36 offset0:64 offset1:80
	ds_write2_b32 v184, v49, v37 offset0:96 offset1:112
	s_waitcnt lgkmcnt(0)
	s_barrier
	ds_read2st64_b32 v[34:35], v172 offset1:8
	ds_read2st64_b32 v[36:37], v172 offset0:16 offset1:24
	ds_read2st64_b32 v[38:39], v172 offset0:32 offset1:40
	s_waitcnt lgkmcnt(2)
	v_add_f32_e32 v34, v188, v34
	v_add_f32_e32 v40, v34, v35
	ds_read2st64_b32 v[34:35], v172 offset0:48 offset1:56
	s_waitcnt lgkmcnt(2)
	v_add_f32_e32 v36, v40, v36
	v_add_f32_e32 v36, v36, v37
	s_waitcnt lgkmcnt(1)
	v_add_f32_e32 v36, v36, v38
	v_add_f32_e32 v36, v36, v39
	s_waitcnt lgkmcnt(0)
	v_add_f32_e32 v34, v36, v34
	v_add_f32_e32 v34, v34, v35
	ds_write_b32 v173, v34
	s_waitcnt lgkmcnt(0)
	s_barrier
	ds_read_b32 v35, v185
	s_waitcnt lgkmcnt(0)
	v_max_f32_e32 v36, v35, v35
	s_waitcnt lgkmcnt(0)
	s_nop 1
	v_max_f32_dpp v34, v35, v36 quad_perm:[1,0,3,2] row_mask:0xf bank_mask:0xf
	s_waitcnt lgkmcnt(0)
	s_nop 1
	v_max_f32_dpp v34, v34, v34 quad_perm:[2,3,0,1] row_mask:0xf bank_mask:0xf
	s_waitcnt lgkmcnt(0)
	s_nop 1
	v_max_f32_dpp v34, v34, v34 row_half_mirror row_mask:0xf bank_mask:0xf
	s_waitcnt lgkmcnt(0)
	s_nop 1
	v_max_f32_dpp v34, v34, v34 row_mirror row_mask:0xf bank_mask:0xf
	ds_bpermute_b32 v36, v155, v34
	s_waitcnt lgkmcnt(0)
	v_max_f32_e32 v36, v36, v36
	v_max_f32_e32 v38, v34, v36
	v_cmp_eq_f32_e32 vcc, v35, v38
	s_nop 1
	v_mov_b32_e32 v34, vcc_hi
	v_mov_b32_e32 v36, vcc_lo
	v_cndmask_b32_e64 v34, v34, v36, s[6:7]
	v_ffbl_b32_e32 v34, v34
	v_cmp_ne_u32_e32 vcc, v1, v34
	s_nop 1
	v_cndmask_b32_e32 v36, v187, v35, vcc
	v_max_f32_e32 v37, v36, v36
	s_waitcnt lgkmcnt(0)
	s_nop 1
	v_max_f32_dpp v35, v36, v37 quad_perm:[1,0,3,2] row_mask:0xf bank_mask:0xf
	s_waitcnt lgkmcnt(0)
	s_nop 1
	v_max_f32_dpp v35, v35, v35 quad_perm:[2,3,0,1] row_mask:0xf bank_mask:0xf
	s_waitcnt lgkmcnt(0)
	s_nop 1
	v_max_f32_dpp v35, v35, v35 row_half_mirror row_mask:0xf bank_mask:0xf
	s_waitcnt lgkmcnt(0)
	s_nop 1
	v_max_f32_dpp v35, v35, v35 row_mirror row_mask:0xf bank_mask:0xf
	ds_bpermute_b32 v37, v155, v35
	s_waitcnt lgkmcnt(0)
	v_max_f32_e32 v37, v37, v37
	v_max_f32_e32 v39, v35, v37
	v_cmp_eq_f32_e32 vcc, v36, v39
	s_nop 1
	v_mov_b32_e32 v35, vcc_hi
	v_mov_b32_e32 v37, vcc_lo
	v_cndmask_b32_e64 v35, v35, v37, s[6:7]
	v_ffbl_b32_e32 v35, v35
	v_cmp_ne_u32_e32 vcc, v1, v35
	s_nop 1
	v_cndmask_b32_e32 v37, v187, v36, vcc
	v_max_f32_e32 v40, v37, v37
	s_waitcnt lgkmcnt(0)
	s_nop 1
	v_max_f32_dpp v36, v37, v40 quad_perm:[1,0,3,2] row_mask:0xf bank_mask:0xf
	s_waitcnt lgkmcnt(0)
	s_nop 1
	v_max_f32_dpp v36, v36, v36 quad_perm:[2,3,0,1] row_mask:0xf bank_mask:0xf
	s_waitcnt lgkmcnt(0)
	s_nop 1
	v_max_f32_dpp v36, v36, v36 row_half_mirror row_mask:0xf bank_mask:0xf
	s_waitcnt lgkmcnt(0)
	s_nop 1
	v_max_f32_dpp v36, v36, v36 row_mirror row_mask:0xf bank_mask:0xf
	ds_bpermute_b32 v40, v155, v36
	s_waitcnt lgkmcnt(0)
	v_max_f32_e32 v40, v40, v40
	v_max_f32_e32 v40, v36, v40
	v_cmp_eq_f32_e32 vcc, v37, v40
	s_nop 1
	v_mov_b32_e32 v36, vcc_hi
	v_mov_b32_e32 v41, vcc_lo
	v_cndmask_b32_e64 v36, v36, v41, s[6:7]
	v_ffbl_b32_e32 v36, v36
	v_cmp_ne_u32_e32 vcc, v1, v36
	s_nop 1
	v_cndmask_b32_e32 v37, v187, v37, vcc
	v_max_f32_e32 v42, v37, v37
	s_waitcnt lgkmcnt(0)
	s_nop 1
	v_max_f32_dpp v41, v37, v42 quad_perm:[1,0,3,2] row_mask:0xf bank_mask:0xf
	s_waitcnt lgkmcnt(0)
	s_nop 1
	v_max_f32_dpp v41, v41, v41 quad_perm:[2,3,0,1] row_mask:0xf bank_mask:0xf
	s_waitcnt lgkmcnt(0)
	s_nop 1
	v_max_f32_dpp v41, v41, v41 row_half_mirror row_mask:0xf bank_mask:0xf
	s_waitcnt lgkmcnt(0)
	s_nop 1
	v_max_f32_dpp v41, v41, v41 row_mirror row_mask:0xf bank_mask:0xf
	ds_bpermute_b32 v42, v155, v41
	s_waitcnt lgkmcnt(0)
	v_max_f32_e32 v42, v42, v42
	v_max_f32_e32 v41, v41, v42
	v_cmp_eq_f32_e32 vcc, v37, v41
	s_and_saveexec_b64 s[10:11], s[8:9]
	s_cbranch_execz .LBB0_1156
	v_mov_b32_e32 v37, vcc_hi
	v_mov_b32_e32 v43, vcc_lo
	v_cndmask_b32_e64 v37, v37, v43, s[6:7]
	v_sub_f32_e32 v43, v38, v38
	v_sub_f32_e32 v39, v39, v38
	v_mul_f32_e32 v43, 0x3fb8aa3b, v43
	v_mul_f32_e32 v39, 0x3fb8aa3b, v39
	v_exp_f32_e32 v44, v43
	v_exp_f32_e32 v45, v39
	v_sub_f32_e32 v39, v40, v38
	v_mul_f32_e32 v39, 0x3fb8aa3b, v39
	v_sub_f32_e32 v38, v41, v38
	v_exp_f32_e32 v40, v39
	v_mul_f32_e32 v38, 0x3fb8aa3b, v38
	v_exp_f32_e32 v41, v38
	v_add_f32_e32 v38, 0, v44
	v_add_f32_e32 v38, v38, v45
	v_add_f32_e32 v38, v38, v40
	v_add_f32_e32 v48, v38, v41
	v_div_scale_f32 v49, s[38:39], v48, v48, 1.0
	v_rcp_f32_e32 v50, v49
	v_add_u32_e32 v42, s35, v162
	v_ashrrev_i32_e32 v43, 31, v42
	v_lshlrev_b64 v[38:39], 4, v[42:43]
	v_lshl_add_u64 v[42:43], s[20:21], 0, v[38:39]
	v_lshl_add_u64 v[46:47], s[22:23], 0, v[38:39]
	v_fma_f32 v38, -v49, v50, 1.0
	v_fmac_f32_e32 v50, v38, v50
	v_div_scale_f32 v38, vcc, 1.0, v48, 1.0
	v_mul_f32_e32 v39, v38, v50
	v_fma_f32 v51, -v49, v39, v38
	v_fmac_f32_e32 v39, v51, v50
	v_fma_f32 v38, -v49, v39, v38
	v_div_fmas_f32 v38, v38, v50, v39
	v_div_fixup_f32 v38, v38, v48, 1.0
	v_ffbl_b32_e32 v37, v37
	v_pk_mul_f32 v[40:41], v[40:41], v[38:39] op_sel_hi:[1,0]
	v_pk_mul_f32 v[38:39], v[44:45], v[38:39] op_sel_hi:[1,0]
	global_store_dwordx4 v[42:43], v[34:37], off
	global_store_dwordx4 v[46:47], v[38:41], off
	s_nop 0
	v_lshl_add_u32 v34, v34, 2, s3
	ds_add_u32 v34, v186
	v_lshl_add_u32 v34, v35, 2, s3
	ds_add_u32 v34, v186
	v_lshl_add_u32 v34, v36, 2, s3
	ds_add_u32 v34, v186
	v_lshl_add_u32 v34, v37, 2, s3
	ds_add_u32 v34, v186
	s_branch .LBB0_1156

.LBB0_1734:
	s_waitcnt vmcnt(39)
	v_lshlrev_b32_e32 v216, 16, v198
	v_and_b32_e32 v217, 0xffff0000, v198
	v_lshlrev_b32_e32 v198, 16, v199
	v_and_b32_e32 v199, 0xffff0000, v199
	v_pk_add_f32 v[198:199], v[198:199], 0 op_sel_hi:[1,0]
	s_waitcnt vmcnt(38)
	v_lshlrev_b32_e32 v218, 16, v196
	v_and_b32_e32 v219, 0xffff0000, v196
	v_lshlrev_b32_e32 v196, 16, v197
	v_and_b32_e32 v197, 0xffff0000, v197
	s_waitcnt vmcnt(31)
	v_lshlrev_b32_e32 v232, 16, v182
	v_and_b32_e32 v233, 0xffff0000, v182
	v_lshlrev_b32_e32 v182, 16, v183
	v_and_b32_e32 v183, 0xffff0000, v183
	v_pk_add_f32 v[196:197], v[196:197], 0 op_sel_hi:[1,0]
	v_lshlrev_b32_e32 v220, 16, v194
	v_and_b32_e32 v221, 0xffff0000, v194
	v_lshlrev_b32_e32 v194, 16, v195
	v_and_b32_e32 v195, 0xffff0000, v195
	v_pk_add_f32 v[182:183], v[198:199], v[182:183]
	s_waitcnt vmcnt(30)
	v_lshlrev_b32_e32 v198, 16, v180
	v_and_b32_e32 v199, 0xffff0000, v180
	v_lshlrev_b32_e32 v180, 16, v181
	v_and_b32_e32 v181, 0xffff0000, v181
	v_pk_add_f32 v[220:221], v[220:221], 0 op_sel_hi:[1,0]
	v_pk_add_f32 v[194:195], v[194:195], 0 op_sel_hi:[1,0]
	v_lshlrev_b32_e32 v222, 16, v192
	v_and_b32_e32 v223, 0xffff0000, v192
	v_lshlrev_b32_e32 v192, 16, v193
	v_and_b32_e32 v193, 0xffff0000, v193
	v_pk_add_f32 v[180:181], v[196:197], v[180:181]
	s_waitcnt vmcnt(29)
	v_lshlrev_b32_e32 v196, 16, v178
	v_and_b32_e32 v197, 0xffff0000, v178
	v_lshlrev_b32_e32 v178, 16, v179
	v_and_b32_e32 v179, 0xffff0000, v179
	v_pk_add_f32 v[192:193], v[192:193], 0 op_sel_hi:[1,0]
	v_lshlrev_b32_e32 v224, 16, v190
	v_and_b32_e32 v225, 0xffff0000, v190
	v_lshlrev_b32_e32 v190, 16, v191
	v_and_b32_e32 v191, 0xffff0000, v191
	v_pk_add_f32 v[178:179], v[194:195], v[178:179]
	v_pk_add_f32 v[194:195], v[220:221], v[196:197]
	s_waitcnt vmcnt(28)
	v_lshlrev_b32_e32 v196, 16, v176
	v_and_b32_e32 v197, 0xffff0000, v176
	v_lshlrev_b32_e32 v176, 16, v177
	v_and_b32_e32 v177, 0xffff0000, v177
	v_pk_add_f32 v[190:191], v[190:191], 0 op_sel_hi:[1,0]
	v_lshlrev_b32_e32 v226, 16, v188
	v_and_b32_e32 v227, 0xffff0000, v188
	v_lshlrev_b32_e32 v188, 16, v189
	v_and_b32_e32 v189, 0xffff0000, v189
	v_pk_add_f32 v[176:177], v[192:193], v[176:177]
	s_waitcnt vmcnt(27)
	v_lshlrev_b32_e32 v192, 16, v174
	v_and_b32_e32 v193, 0xffff0000, v174
	v_lshlrev_b32_e32 v174, 16, v175
	v_and_b32_e32 v175, 0xffff0000, v175
	v_pk_add_f32 v[226:227], v[226:227], 0 op_sel_hi:[1,0]
	v_pk_add_f32 v[188:189], v[188:189], 0 op_sel_hi:[1,0]
	v_lshlrev_b32_e32 v228, 16, v186
	v_and_b32_e32 v229, 0xffff0000, v186
	v_lshlrev_b32_e32 v186, 16, v187
	v_and_b32_e32 v187, 0xffff0000, v187
	v_pk_add_f32 v[174:175], v[190:191], v[174:175]
	s_waitcnt vmcnt(26)
	v_lshlrev_b32_e32 v190, 16, v172
	v_and_b32_e32 v191, 0xffff0000, v172
	v_lshlrev_b32_e32 v172, 16, v173
	v_and_b32_e32 v173, 0xffff0000, v173
	v_pk_add_f32 v[186:187], v[186:187], 0 op_sel_hi:[1,0]
	v_lshlrev_b32_e32 v230, 16, v184
	v_and_b32_e32 v231, 0xffff0000, v184
	v_lshlrev_b32_e32 v184, 16, v185
	v_and_b32_e32 v185, 0xffff0000, v185
	v_pk_add_f32 v[172:173], v[188:189], v[172:173]
	v_pk_add_f32 v[188:189], v[226:227], v[190:191]
	s_waitcnt vmcnt(25)
	v_lshlrev_b32_e32 v190, 16, v170
	v_and_b32_e32 v191, 0xffff0000, v170
	v_lshlrev_b32_e32 v170, 16, v171
	v_and_b32_e32 v171, 0xffff0000, v171
	v_pk_add_f32 v[216:217], v[216:217], 0 op_sel_hi:[1,0]
	v_pk_add_f32 v[184:185], v[184:185], 0 op_sel_hi:[1,0]
	v_pk_add_f32 v[170:171], v[186:187], v[170:171]
	s_waitcnt vmcnt(24)
	v_lshlrev_b32_e32 v186, 16, v168
	v_and_b32_e32 v187, 0xffff0000, v168
	v_lshlrev_b32_e32 v168, 16, v169
	v_and_b32_e32 v169, 0xffff0000, v169
	v_pk_add_f32 v[218:219], v[218:219], 0 op_sel_hi:[1,0]
	v_pk_add_f32 v[216:217], v[216:217], v[232:233]
	v_pk_add_f32 v[168:169], v[184:185], v[168:169]
	s_waitcnt vmcnt(23)
	v_lshlrev_b32_e32 v184, 16, v166
	v_and_b32_e32 v185, 0xffff0000, v166
	v_lshlrev_b32_e32 v166, 16, v167
	v_and_b32_e32 v167, 0xffff0000, v167
	v_pk_add_f32 v[198:199], v[218:219], v[198:199]
	v_pk_add_f32 v[166:167], v[182:183], v[166:167]
	v_pk_add_f32 v[182:183], v[216:217], v[184:185]
	s_waitcnt vmcnt(22)
	v_lshlrev_b32_e32 v184, 16, v164
	v_and_b32_e32 v185, 0xffff0000, v164
	v_lshlrev_b32_e32 v164, 16, v165
	v_and_b32_e32 v165, 0xffff0000, v165
	v_pk_add_f32 v[222:223], v[222:223], 0 op_sel_hi:[1,0]
	v_pk_add_f32 v[164:165], v[180:181], v[164:165]
	v_pk_add_f32 v[180:181], v[198:199], v[184:185]
	s_waitcnt vmcnt(21)
	v_lshlrev_b32_e32 v184, 16, v162
	v_and_b32_e32 v185, 0xffff0000, v162
	v_lshlrev_b32_e32 v162, 16, v163
	v_and_b32_e32 v163, 0xffff0000, v163
	v_pk_add_f32 v[224:225], v[224:225], 0 op_sel_hi:[1,0]
	v_pk_add_f32 v[196:197], v[222:223], v[196:197]
	v_pk_add_f32 v[162:163], v[178:179], v[162:163]
	s_waitcnt vmcnt(20)
	v_lshlrev_b32_e32 v178, 16, v160
	v_and_b32_e32 v179, 0xffff0000, v160
	v_lshlrev_b32_e32 v160, 16, v161
	v_and_b32_e32 v161, 0xffff0000, v161
	v_pk_add_f32 v[192:193], v[224:225], v[192:193]
	v_pk_add_f32 v[160:161], v[176:177], v[160:161]
	v_pk_add_f32 v[176:177], v[196:197], v[178:179]
	s_waitcnt vmcnt(19)
	v_lshlrev_b32_e32 v178, 16, v158
	v_and_b32_e32 v179, 0xffff0000, v158
	v_lshlrev_b32_e32 v158, 16, v159
	v_and_b32_e32 v159, 0xffff0000, v159
	v_pk_add_f32 v[228:229], v[228:229], 0 op_sel_hi:[1,0]
	v_pk_add_f32 v[158:159], v[174:175], v[158:159]
	v_pk_add_f32 v[174:175], v[192:193], v[178:179]
	s_waitcnt vmcnt(18)
	v_lshlrev_b32_e32 v178, 16, v156
	v_and_b32_e32 v179, 0xffff0000, v156
	v_lshlrev_b32_e32 v156, 16, v157
	v_and_b32_e32 v157, 0xffff0000, v157
	v_pk_add_f32 v[230:231], v[230:231], 0 op_sel_hi:[1,0]
	v_pk_add_f32 v[190:191], v[228:229], v[190:191]
	v_pk_add_f32 v[156:157], v[172:173], v[156:157]
	s_waitcnt vmcnt(17)
	v_lshlrev_b32_e32 v172, 16, v154
	v_and_b32_e32 v173, 0xffff0000, v154
	v_lshlrev_b32_e32 v154, 16, v155
	v_and_b32_e32 v155, 0xffff0000, v155
	v_pk_add_f32 v[186:187], v[230:231], v[186:187]
	v_pk_add_f32 v[154:155], v[170:171], v[154:155]
	v_pk_add_f32 v[170:171], v[190:191], v[172:173]
	s_waitcnt vmcnt(16)
	v_lshlrev_b32_e32 v172, 16, v152
	v_and_b32_e32 v173, 0xffff0000, v152
	v_lshlrev_b32_e32 v152, 16, v153
	v_and_b32_e32 v153, 0xffff0000, v153
	v_pk_add_f32 v[152:153], v[168:169], v[152:153]
	v_pk_add_f32 v[168:169], v[186:187], v[172:173]
	s_waitcnt vmcnt(15)
	v_lshlrev_b32_e32 v172, 16, v150
	v_and_b32_e32 v173, 0xffff0000, v150
	v_lshlrev_b32_e32 v150, 16, v151
	v_and_b32_e32 v151, 0xffff0000, v151
	v_pk_add_f32 v[150:151], v[166:167], v[150:151]
	s_waitcnt vmcnt(14)
	v_lshlrev_b32_e32 v166, 16, v148
	v_and_b32_e32 v167, 0xffff0000, v148
	v_lshlrev_b32_e32 v148, 16, v149
	v_and_b32_e32 v149, 0xffff0000, v149
	v_pk_add_f32 v[184:185], v[194:195], v[184:185]
	v_pk_add_f32 v[148:149], v[164:165], v[148:149]
	s_waitcnt vmcnt(13)
	v_lshlrev_b32_e32 v164, 16, v146
	v_and_b32_e32 v165, 0xffff0000, v146
	v_lshlrev_b32_e32 v146, 16, v147
	v_and_b32_e32 v147, 0xffff0000, v147
	v_pk_add_f32 v[146:147], v[162:163], v[146:147]
	v_pk_add_f32 v[162:163], v[184:185], v[164:165]
	s_waitcnt vmcnt(12)
	v_lshlrev_b32_e32 v164, 16, v144
	v_and_b32_e32 v165, 0xffff0000, v144
	v_lshlrev_b32_e32 v144, 16, v145
	v_and_b32_e32 v145, 0xffff0000, v145
	v_pk_add_f32 v[144:145], v[160:161], v[144:145]
	s_waitcnt vmcnt(11)
	v_lshlrev_b32_e32 v160, 16, v142
	v_and_b32_e32 v161, 0xffff0000, v142
	v_lshlrev_b32_e32 v142, 16, v143
	v_and_b32_e32 v143, 0xffff0000, v143
	v_pk_add_f32 v[178:179], v[188:189], v[178:179]
	v_pk_add_f32 v[142:143], v[158:159], v[142:143]
	s_waitcnt vmcnt(10)
	v_lshlrev_b32_e32 v158, 16, v140
	v_and_b32_e32 v159, 0xffff0000, v140
	v_lshlrev_b32_e32 v140, 16, v141
	v_and_b32_e32 v141, 0xffff0000, v141
	v_pk_add_f32 v[140:141], v[156:157], v[140:141]
	v_pk_add_f32 v[156:157], v[178:179], v[158:159]
	s_waitcnt vmcnt(9)
	v_lshlrev_b32_e32 v158, 16, v138
	v_and_b32_e32 v159, 0xffff0000, v138
	v_lshlrev_b32_e32 v138, 16, v139
	v_and_b32_e32 v139, 0xffff0000, v139
	v_pk_add_f32 v[172:173], v[182:183], v[172:173]
	v_pk_add_f32 v[166:167], v[180:181], v[166:167]
	v_pk_add_f32 v[138:139], v[154:155], v[138:139]
	s_waitcnt vmcnt(8)
	v_lshlrev_b32_e32 v154, 16, v136
	v_and_b32_e32 v155, 0xffff0000, v136
	v_lshlrev_b32_e32 v136, 16, v137
	v_and_b32_e32 v137, 0xffff0000, v137
	v_pk_add_f32 v[136:137], v[152:153], v[136:137]
	s_waitcnt vmcnt(7)
	v_pk_fma_f32 v[96:97], v[172:173], v[128:129], v[96:97]
	s_waitcnt vmcnt(6)
	v_pk_fma_f32 v[92:93], v[166:167], v[124:125], v[92:93]
	v_pk_add_f32 v[158:159], v[170:171], v[158:159]
	v_pk_add_f32 v[154:155], v[168:169], v[154:155]
	v_pk_fma_f32 v[98:99], v[150:151], v[130:131], v[98:99]
	v_pk_fma_f32 v[94:95], v[148:149], v[126:127], v[94:95]
	s_waitcnt vmcnt(0)
	v_pk_fma_f32 v[102:103], v[136:137], v[102:103], v[70:71]
	v_mov_b32_e32 v70, v97
	v_mov_b32_e32 v71, v93
	v_pk_fma_f32 v[72:73], v[158:159], v[104:105], v[72:73]
	v_pk_fma_f32 v[100:101], v[154:155], v[100:101], v[68:69]
	v_mov_b32_e32 v68, v96
	v_mov_b32_e32 v69, v92
	v_pk_mul_f32 v[70:71], v[70:71], v[70:71]
	v_mov_b32_e32 v104, v99
	v_mov_b32_e32 v105, v95
	v_pk_fma_f32 v[68:69], v[68:69], v[68:69], v[70:71]
	v_mov_b32_e32 v70, v98
	v_mov_b32_e32 v71, v94
	v_pk_mul_f32 v[104:105], v[104:105], v[104:105]
	v_pk_fma_f32 v[88:89], v[162:163], v[120:121], v[88:89]
	v_pk_fma_f32 v[90:91], v[146:147], v[122:123], v[90:91]
	v_pk_fma_f32 v[70:71], v[70:71], v[70:71], v[104:105]
	v_pk_mul_f32 v[104:105], v[88:89], v[88:89]
	v_pk_add_f32 v[68:69], v[68:69], v[70:71]
	v_pk_mul_f32 v[70:71], v[90:91], v[90:91]
	v_pk_add_f32 v[160:161], v[174:175], v[160:161]
	v_pk_fma_f32 v[74:75], v[138:139], v[106:107], v[74:75]
	v_pk_mov_b32 v[106:107], v[104:105], v[70:71] op_sel:[1,0]
	v_mov_b32_e32 v105, v71
	v_pk_fma_f32 v[80:81], v[160:161], v[112:113], v[80:81]
	v_pk_add_f32 v[70:71], v[106:107], v[104:105]
	v_pk_add_f32 v[164:165], v[176:177], v[164:165]
	v_mul_f32_e32 v104, v80, v80
	v_mul_f32_e32 v105, v81, v81
	v_pk_add_f32 v[68:69], v[68:69], v[68:69] op_sel:[0,1] op_sel_hi:[1,0]
	v_pk_add_f32 v[70:71], v[70:71], v[70:71] op_sel:[0,1] op_sel_hi:[1,0]
	v_pk_fma_f32 v[86:87], v[144:145], v[118:119], v[86:87]
	v_pk_fma_f32 v[84:85], v[164:165], v[116:117], v[84:85]
	v_mov_b32_e32 v69, v104
	v_mov_b32_e32 v71, v105
	v_pk_fma_f32 v[82:83], v[142:143], v[114:115], v[82:83]
	v_pk_add_f32 v[68:69], v[68:69], v[70:71]
	v_mul_f32_e32 v70, v85, v85
	v_mul_f32_e32 v104, v87, v87
	v_mul_f32_e32 v106, v82, v82
	v_mul_f32_e32 v107, v83, v83
	v_pk_fma_f32 v[70:71], v[84:85], v[84:85], v[70:71] op_sel_hi:[1,1,0]
	v_pk_fma_f32 v[104:105], v[86:87], v[86:87], v[104:105] op_sel_hi:[1,1,0]
	v_mov_b32_e32 v71, v106
	v_mov_b32_e32 v105, v107
	v_pk_fma_f32 v[76:77], v[156:157], v[108:109], v[76:77]
	v_pk_fma_f32 v[78:79], v[140:141], v[110:111], v[78:79]
	v_pk_add_f32 v[70:71], v[70:71], v[104:105]
	v_pk_mul_f32 v[104:105], v[76:77], v[76:77]
	v_pk_add_f32 v[68:69], v[68:69], v[70:71]
	v_pk_mul_f32 v[70:71], v[78:79], v[78:79]
	v_pk_add_f32 v[68:69], v[68:69], v[68:69] op_sel:[0,1] op_sel_hi:[1,0]
	v_pk_mov_b32 v[106:107], v[104:105], v[70:71] op_sel:[1,0]
	v_mov_b32_e32 v105, v71
	v_pk_add_f32 v[70:71], v[106:107], v[104:105]
	v_mul_f32_e32 v104, v100, v100
	v_mul_f32_e32 v105, v101, v101
	v_pk_add_f32 v[70:71], v[70:71], v[70:71] op_sel:[0,1] op_sel_hi:[1,0]
	v_mov_b32_e32 v69, v104
	v_mov_b32_e32 v71, v105
	v_pk_add_f32 v[68:69], v[68:69], v[70:71]
	v_mul_f32_e32 v70, v73, v73
	v_mul_f32_e32 v104, v75, v75
	v_mul_f32_e32 v106, v102, v102
	v_mul_f32_e32 v107, v103, v103
	v_pk_fma_f32 v[70:71], v[72:73], v[72:73], v[70:71] op_sel_hi:[1,1,0]
	v_pk_fma_f32 v[104:105], v[74:75], v[74:75], v[104:105] op_sel_hi:[1,1,0]
	v_mov_b32_e32 v71, v106
	v_mov_b32_e32 v105, v107
	v_pk_add_f32 v[70:71], v[70:71], v[104:105]
	v_lshl_add_u64 v[106:107], s[4:5], 0, v[132:133]
	v_pk_add_f32 v[68:69], v[68:69], v[70:71]
	s_add_u32 s4, s4, s6
	v_add_f32_e32 v68, v68, v69
	s_addc_u32 s5, s5, s7
	s_add_u32 s8, s8, s6
	s_addc_u32 s9, s9, s7
	s_add_u32 s10, s10, s12
	s_waitcnt lgkmcnt(0)
	s_nop 1
	v_add_f32_dpp v68, v68, v68 quad_perm:[1,0,3,2] row_mask:0xf bank_mask:0xf
	s_addc_u32 s11, s11, s13
	s_waitcnt lgkmcnt(0)
	s_nop 1
	v_add_f32_dpp v68, v68, v68 quad_perm:[2,3,0,1] row_mask:0xf bank_mask:0xf
	s_waitcnt lgkmcnt(0)
	s_nop 1
	v_add_f32_dpp v68, v68, v68 row_half_mirror row_mask:0xf bank_mask:0xf
	ds_bpermute_b32 v69, v203, v68
	s_waitcnt lgkmcnt(0)
	v_add_f32_e32 v68, v68, v69
	ds_bpermute_b32 v69, v204, v68
	s_waitcnt lgkmcnt(0)
	v_add_f32_e32 v68, v68, v69
	ds_bpermute_b32 v69, v205, v68
	s_waitcnt lgkmcnt(0)
	v_add_f32_e32 v68, v68, v69
	v_fmamk_f32 v68, v68, 0x3a000000, v214
	v_mul_f32_e32 v69, 0x4f800000, v68
	v_cmp_gt_f32_e32 vcc, s16, v68
	s_nop 1
	v_cndmask_b32_e32 v68, v68, v69, vcc
	v_sqrt_f32_e32 v69, v68
	s_nop 0
	v_add_u32_e32 v70, -1, v69
	v_fma_f32 v71, -v70, v69, v68
	v_cmp_ge_f32_e64 s[0:1], 0, v71
	v_add_u32_e32 v71, 1, v69
	s_nop 0
	v_cndmask_b32_e64 v70, v69, v70, s[0:1]
	v_fma_f32 v69, -v71, v69, v68
	v_cmp_lt_f32_e64 s[0:1], 0, v69
	s_nop 1
	v_cndmask_b32_e64 v69, v70, v71, s[0:1]
	v_mul_f32_e32 v70, 0x37800000, v69
	v_cndmask_b32_e32 v69, v69, v70, vcc
	v_cmp_class_f32_e32 vcc, v68, v215
	s_nop 1
	v_cndmask_b32_e32 v68, v69, v68, vcc
	v_div_scale_f32 v69, s[0:1], v68, v68, 1.0
	v_rcp_f32_e32 v70, v69
	s_nop 0
	v_fma_f32 v71, -v69, v70, 1.0
	v_fmac_f32_e32 v70, v71, v70
	v_div_scale_f32 v71, vcc, 1.0, v68, 1.0
	v_mul_f32_e32 v104, v71, v70
	v_fma_f32 v105, -v69, v104, v71
	v_fmac_f32_e32 v104, v105, v70
	v_fma_f32 v69, -v69, v104, v71
	v_div_fmas_f32 v69, v69, v70, v104
	v_div_fixup_f32 v104, v69, v68, 1.0
	v_pk_mul_f32 v[68:69], v[96:97], v[104:105] op_sel_hi:[1,0]
	v_pk_mul_f32 v[70:71], v[98:99], v[104:105] op_sel_hi:[1,0]
	v_pk_mul_f32 v[68:69], v[28:29], v[68:69]
	v_pk_mul_f32 v[70:71], v[30:31], v[70:71]
	global_store_dwordx4 v[106:107], v[68:71], off
	v_mov_b64_e32 v[98:99], v[50:51]
	v_mov_b64_e32 v[96:97], v[48:49]
	v_pk_mul_f32 v[68:69], v[92:93], v[104:105] op_sel_hi:[1,0]
	v_pk_mul_f32 v[70:71], v[94:95], v[104:105] op_sel_hi:[1,0]
	v_pk_mul_f32 v[68:69], v[0:1], v[68:69]
	v_pk_mul_f32 v[70:71], v[2:3], v[70:71]
	global_store_dwordx4 v[106:107], v[68:71], off offset:1024
	v_mov_b64_e32 v[94:95], v[46:47]
	v_mov_b64_e32 v[92:93], v[44:45]
	v_pk_mul_f32 v[68:69], v[88:89], v[104:105] op_sel_hi:[1,0]
	v_pk_mul_f32 v[70:71], v[90:91], v[104:105] op_sel_hi:[1,0]
	v_pk_mul_f32 v[68:69], v[4:5], v[68:69]
	v_pk_mul_f32 v[70:71], v[6:7], v[70:71]
	global_store_dwordx4 v[106:107], v[68:71], off offset:2048
	v_mov_b64_e32 v[90:91], v[42:43]
	v_mov_b64_e32 v[88:89], v[40:41]
	v_pk_mul_f32 v[68:69], v[84:85], v[104:105] op_sel_hi:[1,0]
	v_pk_mul_f32 v[70:71], v[86:87], v[104:105] op_sel_hi:[1,0]
	v_pk_mul_f32 v[68:69], v[8:9], v[68:69]
	v_pk_mul_f32 v[70:71], v[10:11], v[70:71]
	global_store_dwordx4 v[106:107], v[68:71], off offset:3072
	v_mov_b64_e32 v[86:87], v[38:39]
	v_mov_b64_e32 v[84:85], v[36:37]
	v_pk_mul_f32 v[68:69], v[80:81], v[104:105] op_sel_hi:[1,0]
	v_pk_mul_f32 v[70:71], v[82:83], v[104:105] op_sel_hi:[1,0]
	v_add_co_u32_e32 v80, vcc, s17, v106
	v_pk_mul_f32 v[70:71], v[26:27], v[70:71]
	v_pk_mul_f32 v[68:69], v[24:25], v[68:69]
	v_addc_co_u32_e32 v81, vcc, 0, v107, vcc
	global_store_dwordx4 v[80:81], v[68:71], off
	s_andn2_b64 vcc, exec, s[14:15]
	s_nop 0
	v_pk_mul_f32 v[68:69], v[76:77], v[104:105] op_sel_hi:[1,0]
	v_pk_mul_f32 v[70:71], v[78:79], v[104:105] op_sel_hi:[1,0]
	v_pk_mul_f32 v[68:69], v[20:21], v[68:69]
	v_pk_mul_f32 v[70:71], v[22:23], v[70:71]
	global_store_dwordx4 v[80:81], v[68:71], off offset:1024
	v_mov_b64_e32 v[78:79], v[62:63]
	v_mov_b64_e32 v[76:77], v[60:61]
	v_pk_mul_f32 v[68:69], v[72:73], v[104:105] op_sel_hi:[1,0]
	v_pk_mul_f32 v[70:71], v[74:75], v[104:105] op_sel_hi:[1,0]
	v_pk_mul_f32 v[68:69], v[16:17], v[68:69]
	v_pk_mul_f32 v[70:71], v[18:19], v[70:71]
	global_store_dwordx4 v[80:81], v[68:71], off offset:2048
	v_mov_b64_e32 v[74:75], v[58:59]
	v_mov_b64_e32 v[72:73], v[56:57]
	v_pk_mul_f32 v[68:69], v[100:101], v[104:105] op_sel_hi:[1,0]
	v_pk_mul_f32 v[70:71], v[102:103], v[104:105] op_sel_hi:[1,0]
	v_pk_mul_f32 v[68:69], v[12:13], v[68:69]
	v_pk_mul_f32 v[70:71], v[14:15], v[70:71]
	global_store_dwordx4 v[80:81], v[68:71], off offset:3072
	v_mov_b64_e32 v[82:83], v[66:67]
	v_mov_b64_e32 v[80:81], v[64:65]
	v_mov_b64_e32 v[70:71], v[54:55]
	v_mov_b64_e32 v[68:69], v[52:53]
	s_cbranch_vccz .LBB0_1737
